# stack: in-place attention accumulators + packed f32 split in attention phase, on top of best PEER version
# speedup vs baseline: 1.0067x; 1.0008x over previous
.LBB0_1416:
	v_lshrrev_b32_e32 v3, s42, v159
	v_and_b32_e32 v3, 1, v3
	v_cmp_eq_u32_e64 s[2:3], 1, v3
	s_or_b64 s[8:9], s[28:29], s[2:3]
	v_cndmask_b32_e64 v3, 0, 1, s[8:9]
	v_cmp_ne_u32_e32 vcc, 0, v3
	s_cbranch_vccz .LBB0_1443
	s_cmp_lt_i32 s42, s48
	s_cselect_b64 s[24:25], -1, 0
	s_cmp_ge_i32 s42, s48
	s_cselect_b64 s[30:31], -1, 0
	s_mov_b64 s[26:27], -1
	s_and_b64 vcc, exec, s[20:21]
	v_lshl_or_b32 v165, s42, 6, v136
	s_cbranch_vccz .LBB0_1426
	v_sub_u32_e32 v68, v161, v165
	v_cvt_f32_i32_e32 v221, v68
	v_add_u32_e32 v219, s38, v176
	s_and_b64 vcc, exec, s[30:31]
	v_add_u32_e32 v69, v219, v177
	v_add_u32_e32 v220, v219, v178
	s_cbranch_vccz .LBB0_1422
	v_mov_b32_e32 v3, v157
	ds_read_b128 v[52:55], v69
	ds_read_b128 v[56:59], v69 offset:32
	v_mul_f32_e64 v36, v221, -v3
	v_cndmask_b32_e64 v66, v214, v36, s[2:3]
	v_mov_b32_e32 v74, v3
	v_fma_f32 v38, 0, v3, v66
	v_fmamk_f32 v42, v3, 0x41000000, v66
	v_fmamk_f32 v46, v3, 0x41800000, v66
	v_fmamk_f32 v50, v3, 0x41c00000, v66
	v_add_f32_e32 v36, v2, v38
	v_add_f32_e32 v37, v3, v38
	v_fma_f32 v39, v74, s65, v38
	v_fma_f32 v38, v74, s64, v38
	v_add_f32_e32 v40, v2, v42
	v_add_f32_e32 v41, v3, v42
	v_fma_f32 v43, v74, s65, v42
	v_fma_f32 v42, v74, s64, v42
	v_add_f32_e32 v44, v2, v46
	v_add_f32_e32 v45, v3, v46
	v_fma_f32 v47, v74, s65, v46
	v_fma_f32 v46, v74, s64, v46
	v_add_f32_e32 v48, v2, v50
	v_add_f32_e32 v49, v3, v50
	v_fma_f32 v51, v74, s65, v50
	v_fma_f32 v50, v74, s64, v50
	v_fmamk_f32 v62, v3, 0x42200000, v66
	v_fmamk_f32 v64, v3, 0x42400000, v66
	s_waitcnt lgkmcnt(1)
	v_mfma_f32_32x32x16_bf16 v[36:51], v[52:55], v[100:103], v[36:51]
	v_cmp_lt_i32_e32 vcc, -1, v68
	s_waitcnt lgkmcnt(0)
	v_mfma_f32_32x32x16_bf16 v[36:51], v[56:59], v[104:107], v[36:51]
	ds_read_b128 v[52:55], v69 offset:64
	ds_read_b128 v[58:61], v69 offset:96
	ds_read_b128 v[70:73], v220
	v_add_f32_e64 v56, v2, v62
	v_add_f32_e64 v57, v3, v62
	s_waitcnt lgkmcnt(2)
	v_mfma_f32_32x32x16_bf16 v[36:51], v[52:55], v[108:111], v[36:51]
	v_fmamk_f32 v54, v3, 0x42000000, v66
	v_fmac_f32_e32 v66, 0x42600000, v3
	v_add_f32_e64 v52, v2, v54
	v_add_f32_e64 v53, v3, v54
	v_fma_f32 v55, v74, s65, v54
	v_fma_f32 v54, v74, s64, v54
	s_waitcnt lgkmcnt(1)
	v_mfma_f32_32x32x16_bf16 v[36:51], v[58:61], v[112:115], v[36:51]
	v_fma_f32 v58, v74, s64, v62
	v_fma_f32 v59, v74, s65, v62
	v_add_f32_e64 v60, v2, v64
	v_add_f32_e64 v61, v3, v64
	v_fma_f32 v62, v74, s64, v64
	v_fma_f32 v63, v74, s65, v64
	v_add_f32_e32 v64, v2, v66
	v_add_f32_e32 v65, v3, v66
	v_fma_f32 v67, v74, s65, v66
	v_fma_f32 v66, v74, s64, v66
	ds_read_b128 v[74:77], v220 offset:32
	s_nop 2
	v_cndmask_b32_e32 v86, v214, v36, vcc
	s_waitcnt lgkmcnt(1)
	v_mfma_f32_32x32x16_bf16 v[52:67], v[70:73], v[100:103], v[52:67]
	ds_read_b128 v[70:73], v220 offset:64
	ds_read_b128 v[78:81], v220 offset:96
	v_cmp_lt_i32_e32 vcc, 0, v68
	s_nop 1
	v_cndmask_b32_e32 v87, v214, v37, vcc
	v_cmp_lt_i32_e32 vcc, 1, v68
	v_max3_f32 v3, v86, s97, v87
	s_waitcnt lgkmcnt(2)
	v_mfma_f32_32x32x16_bf16 v[52:67], v[74:77], v[104:107], v[52:67]
	v_cndmask_b32_e32 v94, v214, v38, vcc
	v_cmp_lt_i32_e32 vcc, 2, v68
	s_nop 1
	v_cndmask_b32_e32 v95, v214, v39, vcc
	v_cmp_lt_i32_e32 vcc, 7, v68
	v_max3_f32 v3, v3, v94, v95
	s_waitcnt lgkmcnt(1)
	v_mfma_f32_32x32x16_bf16 v[52:67], v[70:73], v[108:111], v[52:67]
	v_cndmask_b32_e32 v98, v214, v40, vcc
	v_cmp_lt_i32_e32 vcc, 8, v68
	s_nop 1
	v_cndmask_b32_e32 v99, v214, v41, vcc
	v_cmp_lt_i32_e32 vcc, 9, v68
	v_max3_f32 v3, v3, v98, v99
	s_waitcnt lgkmcnt(0)
	v_mfma_f32_32x32x16_bf16 v[52:67], v[78:81], v[112:115], v[52:67]
	v_cndmask_b32_e32 v96, v214, v42, vcc
	v_cmp_lt_i32_e32 vcc, 10, v68
	s_nop 1
	v_cndmask_b32_e32 v97, v214, v43, vcc
	v_cmp_lt_i32_e32 vcc, 15, v68
	v_max3_f32 v3, v3, v96, v97
	s_nop 0
	v_cndmask_b32_e32 v170, v214, v44, vcc
	v_cmp_lt_i32_e32 vcc, 16, v68
	s_nop 1
	v_cndmask_b32_e32 v171, v214, v45, vcc
	v_cmp_lt_i32_e32 vcc, 17, v68
	v_max3_f32 v3, v3, v170, v171
	s_nop 0
	v_cndmask_b32_e32 v90, v214, v46, vcc
	v_cmp_lt_i32_e32 vcc, 18, v68
	s_nop 1
	v_cndmask_b32_e32 v91, v214, v47, vcc
	v_cmp_lt_i32_e32 vcc, 23, v68
	v_max3_f32 v3, v3, v90, v91
	s_nop 0
	v_cndmask_b32_e32 v92, v214, v48, vcc
	v_cmp_lt_i32_e32 vcc, 24, v68
	s_nop 1
	v_cndmask_b32_e32 v93, v214, v49, vcc
	v_cmp_lt_i32_e32 vcc, 25, v68
	v_max3_f32 v3, v3, v92, v93
	s_nop 0
	v_cndmask_b32_e32 v88, v214, v50, vcc
	v_cmp_lt_i32_e32 vcc, 26, v68
	s_nop 1
	v_cndmask_b32_e32 v89, v214, v51, vcc
	v_cmp_lt_i32_e32 vcc, 31, v68
	v_max3_f32 v3, v3, v88, v89
	s_nop 0
	v_cndmask_b32_e32 v84, v214, v52, vcc
	v_cmp_lt_i32_e32 vcc, 32, v68
	s_nop 1
	v_cndmask_b32_e32 v85, v214, v53, vcc
	v_cmp_lt_i32_e32 vcc, 33, v68
	v_max3_f32 v3, v3, v84, v85
	s_nop 0
	v_cndmask_b32_e32 v82, v214, v54, vcc
	v_cmp_lt_i32_e32 vcc, 34, v68
	s_nop 1
	v_cndmask_b32_e32 v83, v214, v55, vcc
	v_cmp_lt_i32_e32 vcc, 39, v68
	v_max3_f32 v3, v3, v82, v83
	s_nop 0
	v_cndmask_b32_e32 v80, v214, v56, vcc
	v_cmp_lt_i32_e32 vcc, 40, v68
	s_nop 1
	v_cndmask_b32_e32 v81, v214, v57, vcc
	v_cmp_lt_i32_e32 vcc, 41, v68
	v_max3_f32 v3, v3, v80, v81
	s_nop 0
	v_cndmask_b32_e32 v78, v214, v58, vcc
	v_cmp_lt_i32_e32 vcc, 42, v68
	s_nop 1
	v_cndmask_b32_e32 v79, v214, v59, vcc
	v_cmp_lt_i32_e32 vcc, 47, v68
	v_max3_f32 v3, v3, v78, v79
	s_nop 0
	v_cndmask_b32_e32 v76, v214, v60, vcc
	v_cmp_lt_i32_e32 vcc, 48, v68
	s_nop 1
	v_cndmask_b32_e32 v77, v214, v61, vcc
	v_cmp_lt_i32_e32 vcc, 49, v68
	v_max3_f32 v3, v3, v76, v77
	s_nop 0
	v_cndmask_b32_e32 v74, v214, v62, vcc
	v_cmp_lt_i32_e32 vcc, 50, v68
	s_nop 1
	v_cndmask_b32_e32 v75, v214, v63, vcc
	v_cmp_lt_i32_e32 vcc, 55, v68
	v_max3_f32 v3, v3, v74, v75
	s_nop 0
	v_cndmask_b32_e32 v70, v214, v64, vcc
	v_cmp_lt_i32_e32 vcc, 56, v68
	s_nop 1
	v_cndmask_b32_e32 v71, v214, v65, vcc
	v_cmp_lt_i32_e32 vcc, 57, v68
	v_max3_f32 v3, v3, v70, v71
	s_nop 0
	v_cndmask_b32_e32 v72, v214, v66, vcc
	v_cmp_lt_i32_e32 vcc, 58, v68
	s_nop 1
	v_cndmask_b32_e32 v73, v214, v67, vcc
	v_max3_f32 v3, v3, v72, v73
	ds_bpermute_b32 v36, v179, v3
	s_nop 3
	s_waitcnt lgkmcnt(0)
	v_max_f32_e32 v36, v36, v36
	v_max_f32_e32 v3, v3, v36
	v_max3_f32 v132, v218, v3, s46
	v_sub_f32_e32 v3, v218, v132
	v_exp_f32_e32 v68, v3
	s_nop 2
	v_cmp_eq_f32_e32 vcc, 1.0, v68
	s_cmp_eq_u64 vcc, exec
	s_nop 8
	s_cbranch_scc1 .LBB0_1421
	v_mul_f32_e32 v34, v34, v68
	v_mul_f32_e32 v35, v35, v68
	v_mul_f32_e32 v32, v32, v68
	v_mul_f32_e32 v33, v33, v68
	v_mul_f32_e32 v30, v30, v68
	v_mul_f32_e32 v31, v31, v68
	v_mul_f32_e32 v28, v28, v68
	v_mul_f32_e32 v29, v29, v68
	v_mul_f32_e32 v26, v26, v68
	v_mul_f32_e32 v27, v27, v68
	v_mul_f32_e32 v24, v24, v68
	v_mul_f32_e32 v25, v25, v68
	v_mul_f32_e32 v22, v22, v68
	v_mul_f32_e32 v23, v23, v68
	v_mul_f32_e32 v20, v20, v68
	v_mul_f32_e32 v21, v21, v68
	v_mul_f32_e32 v18, v18, v68
	v_mul_f32_e32 v19, v19, v68
	v_mul_f32_e32 v16, v16, v68
	v_mul_f32_e32 v17, v17, v68
	v_mul_f32_e32 v14, v14, v68
	v_mul_f32_e32 v15, v15, v68
	v_mul_f32_e32 v12, v12, v68
	v_mul_f32_e32 v13, v13, v68
	v_mul_f32_e32 v10, v10, v68
	v_mul_f32_e32 v11, v11, v68
	v_mul_f32_e32 v8, v8, v68
	v_mul_f32_e32 v9, v9, v68
	v_mul_f32_e32 v6, v6, v68
	v_mul_f32_e32 v7, v7, v68
	v_mul_f32_e32 v4, v4, v68
	v_mul_f32_e32 v5, v5, v68
.LBB0_1421:
	v_sub_f32_e32 v94, v94, v132
	v_sub_f32_e32 v95, v95, v132
	v_lshl_add_u32 v3, v136, 1, s38
	v_exp_f32_e32 v230, v94
	v_exp_f32_e32 v231, v95
	v_sub_f32_e32 v94, v98, v132
	v_sub_f32_e32 v95, v99, v132
	v_sub_f32_e32 v86, v86, v132
	v_sub_f32_e32 v87, v87, v132
	v_exp_f32_e32 v98, v94
	v_exp_f32_e32 v99, v95
	v_sub_f32_e32 v94, v96, v132
	v_sub_f32_e32 v95, v97, v132
	v_exp_f32_e32 v86, v86
	v_exp_f32_e32 v232, v94
	v_add_u32_e32 v94, v3, v190
	v_add_u32_e32 v186, 0x2000, v94
	v_exp_f32_e32 v233, v95
	ds_read2_b64 v[94:97], v186 offset0:128 offset1:130
	v_add_u32_e32 v3, v3, v191
	v_add_u32_e32 v3, 0x2000, v3
	ds_read2_b64 v[226:229], v3 offset0:128 offset1:130
	v_exp_f32_e32 v87, v87
	v_sub_f32_e32 v90, v90, v132
	v_sub_f32_e32 v91, v91, v132
	v_cvt_pk_bf16_f32 v223, v230, v231
	v_exp_f32_e32 v234, v90
	v_exp_f32_e32 v235, v91
	v_sub_f32_e32 v90, v92, v132
	v_sub_f32_e32 v91, v93, v132
	v_cvt_pk_bf16_f32 v222, v86, v87
	v_cvt_pk_bf16_f32 v224, v98, v99
	v_cvt_pk_bf16_f32 v225, v232, v233
	v_exp_f32_e32 v236, v90
	v_exp_f32_e32 v237, v91
	ds_read2_b64 v[90:93], v186 offset0:132 offset1:134
	s_waitcnt lgkmcnt(2)
	v_mfma_f32_32x32x16_bf16 v[20:35], v[94:97], v[222:225], v[20:35]
	v_add_f32_e64 v170, v170, -v132
	v_add_f32_e64 v171, v171, -v132
	v_add_f32_e64 v88, v88, -v132
	v_add_f32_e64 v89, v89, -v132
	v_exp_f32_e32 v170, v170
	v_exp_f32_e32 v171, v171
	v_cvt_pk_bf16_f32 v95, v234, v235
	v_cvt_pk_bf16_f32 v96, v236, v237
	v_cvt_pk_bf16_f32 v94, v170, v171
	s_waitcnt lgkmcnt(1)
	v_mfma_f32_32x32x16_bf16 v[4:19], v[226:229], v[222:225], v[4:19]
	v_exp_f32_e32 v222, v88
	v_exp_f32_e32 v223, v89
	s_nop 0
	v_cvt_pk_bf16_f32 v97, v222, v223
	s_waitcnt lgkmcnt(0)
	s_nop 0
	v_mfma_f32_32x32x16_bf16 v[20:35], v[90:93], v[94:97], v[20:35]
	ds_read2_b64 v[88:91], v3 offset0:132 offset1:134
	s_waitcnt lgkmcnt(0)
	v_mfma_f32_32x32x16_bf16 v[4:19], v[88:91], v[94:97], v[4:19]
	v_add_f32_e64 v80, v80, -v132
	v_add_f32_e64 v81, v81, -v132
	v_add_f32_e64 v78, v78, -v132
	v_add_f32_e64 v79, v79, -v132
	v_exp_f32_e32 v94, v80
	v_exp_f32_e32 v95, v81
	v_exp_f32_e32 v96, v78
	v_exp_f32_e32 v97, v79
	v_sub_f32_e32 v80, v76, v132
	v_sub_f32_e32 v81, v77, v132
	ds_read2_b64 v[76:79], v186 offset0:136 offset1:138
	v_sub_f32_e32 v84, v84, v132
	v_sub_f32_e32 v85, v85, v132
	v_sub_f32_e32 v82, v82, v132
	v_sub_f32_e32 v83, v83, v132
	ds_read2_b64 v[88:91], v3 offset0:136 offset1:138
	v_exp_f32_e32 v84, v84
	v_exp_f32_e32 v85, v85
	v_exp_f32_e32 v92, v82
	v_exp_f32_e32 v93, v83
	v_sub_f32_e32 v74, v74, v132
	v_sub_f32_e32 v75, v75, v132
	v_sub_f32_e32 v70, v70, v132
	v_sub_f32_e32 v71, v71, v132
	v_exp_f32_e32 v224, v80
	v_exp_f32_e32 v225, v81
	v_cvt_pk_bf16_f32 v80, v84, v85
	v_cvt_pk_bf16_f32 v81, v92, v93
	v_cvt_pk_bf16_f32 v82, v94, v95
	v_cvt_pk_bf16_f32 v83, v96, v97
	v_exp_f32_e32 v226, v74
	v_exp_f32_e32 v227, v75
	v_exp_f32_e32 v228, v70
	v_exp_f32_e32 v229, v71
	v_sub_f32_e32 v74, v72, v132
	v_sub_f32_e32 v75, v73, v132
	ds_read2_b64 v[70:73], v186 offset0:140 offset1:142
	s_waitcnt lgkmcnt(2)
	v_mfma_f32_32x32x16_bf16 v[20:35], v[76:79], v[80:83], v[20:35]
	v_cvt_pk_bf16_f32 v78, v224, v225
	v_cvt_pk_bf16_f32 v79, v226, v227
	s_mov_b64 s[26:27], 0
	s_waitcnt lgkmcnt(1)
	v_mfma_f32_32x32x16_bf16 v[4:19], v[88:91], v[80:83], v[4:19]
	v_exp_f32_e32 v82, v74
	v_exp_f32_e32 v83, v75
	v_cvt_pk_bf16_f32 v80, v228, v229
	ds_read2_b64 v[74:77], v3 offset0:140 offset1:142
	v_cvt_pk_bf16_f32 v81, v82, v83
	s_waitcnt lgkmcnt(1)
	s_nop 0
	v_mfma_f32_32x32x16_bf16 v[20:35], v[70:73], v[78:81], v[20:35]
	v_add_f32_e64 v70, v86, 0
	v_add_f32_e64 v71, v87, 0
	v_add_f32_e64 v70, v230, v70
	v_add_f32_e64 v71, v231, v71
	v_add_f32_e64 v70, v98, v70
	v_add_f32_e64 v71, v99, v71
	v_add_f32_e32 v70, v232, v70
	v_add_f32_e32 v71, v233, v71
	s_waitcnt lgkmcnt(0)
	v_mfma_f32_32x32x16_bf16 v[4:19], v[74:77], v[78:81], v[4:19]
	v_add_f32_e64 v70, v170, v70
	v_add_f32_e64 v71, v171, v71
	v_add_f32_e64 v70, v234, v70
	v_add_f32_e64 v71, v235, v71
	v_add_f32_e64 v70, v236, v70
	v_add_f32_e64 v71, v237, v71
	v_add_f32_e32 v70, v222, v70
	v_add_f32_e32 v71, v223, v71
	s_nop 0
	v_add_f32_e32 v70, v84, v70
	v_add_f32_e32 v71, v85, v71
	s_nop 0
	v_add_f32_e32 v70, v92, v70
	v_add_f32_e32 v71, v93, v71
	s_nop 0
	v_add_f32_e32 v70, v94, v70
	v_add_f32_e32 v71, v95, v71
	s_nop 0
	v_add_f32_e32 v70, v96, v70
	v_add_f32_e32 v71, v97, v71
	s_nop 0
	v_add_f32_e32 v70, v224, v70
	v_add_f32_e32 v71, v225, v71
	s_nop 0
	v_add_f32_e32 v70, v226, v70
	v_add_f32_e32 v71, v227, v71
	s_nop 0
	v_add_f32_e32 v70, v228, v70
	v_add_f32_e32 v71, v229, v71
	s_nop 0
	v_add_f32_e32 v70, v82, v70
	v_add_f32_e32 v71, v83, v71
	s_nop 0
	v_add_f32_e32 v3, v70, v71
	ds_bpermute_b32 v70, v179, v3
	s_waitcnt lgkmcnt(0)
	v_add_f32_e32 v3, v3, v70
	v_fmac_f32_e32 v3, v217, v68
.LBB0_1422:
	s_and_b64 vcc, exec, s[26:27]
	s_cbranch_vccz .LBB0_1441
	v_mov_b32_e32 v3, v157
	s_nop 0
	v_mul_f32_e64 v36, v221, -v3
	v_cndmask_b32_e64 v44, v214, v36, s[2:3]
	v_mov_b32_e32 v46, v3
	v_fma_f32 v36, 0, v3, v44
	v_add_f32_e32 v84, v2, v36
	v_add_f32_e32 v85, v3, v36
	v_fma_f32 v86, v46, s64, v36
	v_fma_f32 v87, v46, s65, v36
	ds_read_b128 v[36:39], v69
	v_fmamk_f32 v40, v3, 0x41000000, v44
	v_add_f32_e32 v88, v2, v40
	v_add_f32_e32 v89, v3, v40
	v_fma_f32 v90, v46, s64, v40
	v_fma_f32 v91, v46, s65, v40
	v_fmamk_f32 v40, v3, 0x41800000, v44
	v_add_f32_e32 v92, v2, v40
	v_add_f32_e32 v93, v3, v40
	v_fma_f32 v94, v46, s64, v40
	v_fma_f32 v95, v46, s65, v40
	v_fmamk_f32 v40, v3, 0x41c00000, v44
	v_add_f32_e32 v96, v2, v40
	v_add_f32_e32 v97, v3, v40
	v_fma_f32 v98, v46, s64, v40
	v_fma_f32 v99, v46, s65, v40
	ds_read_b128 v[40:43], v69 offset:32
	v_fmamk_f32 v48, v3, 0x42000000, v44
	s_waitcnt lgkmcnt(1)
	v_mfma_f32_32x32x16_bf16 v[84:99], v[36:39], v[100:103], v[84:99]
	v_fmamk_f32 v50, v3, 0x42200000, v44
	v_fmamk_f32 v52, v3, 0x42400000, v44
	v_fmac_f32_e32 v44, 0x42600000, v3
	v_fma_f32 v70, v46, s64, v48
	v_fma_f32 v71, v46, s65, v48
	v_add_f32_e32 v72, v2, v50
	v_add_f32_e32 v73, v3, v50
	v_fma_f32 v74, v46, s64, v50
	v_fma_f32 v75, v46, s65, v50
	v_add_f32_e32 v76, v2, v52
	v_add_f32_e32 v77, v3, v52
	s_waitcnt lgkmcnt(0)
	v_mfma_f32_32x32x16_bf16 v[84:99], v[40:43], v[104:107], v[84:99]
	ds_read_b128 v[36:39], v69 offset:64
	ds_read_b128 v[40:43], v69 offset:96
	v_add_f32_e64 v68, v2, v48
	v_add_f32_e64 v69, v3, v48
	v_fma_f32 v78, v46, s64, v52
	v_fma_f32 v79, v46, s65, v52
	v_add_f32_e32 v80, v2, v44
	v_add_f32_e32 v81, v3, v44
	v_fma_f32 v82, v46, s64, v44
	v_fma_f32 v83, v46, s65, v44
	s_nop 1
	s_waitcnt lgkmcnt(1)
	v_mfma_f32_32x32x16_bf16 v[84:99], v[36:39], v[108:111], v[84:99]
	ds_read_b128 v[36:39], v220
	s_nop 5
	s_waitcnt lgkmcnt(1)
	v_mfma_f32_32x32x16_bf16 v[84:99], v[40:43], v[112:115], v[84:99]
	ds_read_b128 v[40:43], v220 offset:32
	s_waitcnt lgkmcnt(1)
	v_mfma_f32_32x32x16_bf16 v[68:83], v[36:39], v[100:103], v[68:83]
	s_nop 8
	v_max3_f32 v3, v84, s97, v85
	v_max3_f32 v3, v3, v86, v87
	v_max3_f32 v3, v3, v88, v89
	v_max3_f32 v3, v3, v90, v91
	v_max3_f32 v3, v3, v92, v93
	v_max3_f32 v3, v3, v94, v95
	v_max3_f32 v3, v3, v96, v97
	s_waitcnt lgkmcnt(0)
	v_mfma_f32_32x32x16_bf16 v[68:83], v[40:43], v[104:107], v[68:83]
	ds_read_b128 v[36:39], v220 offset:64
	ds_read_b128 v[40:43], v220 offset:96
	v_max3_f32 v3, v3, v98, v99
	s_waitcnt lgkmcnt(1)
	v_mfma_f32_32x32x16_bf16 v[68:83], v[36:39], v[108:111], v[68:83]
	s_waitcnt lgkmcnt(0)
	v_mfma_f32_32x32x16_bf16 v[68:83], v[40:43], v[112:115], v[68:83]
	s_nop 11
	v_max3_f32 v3, v3, v68, v69
	v_max3_f32 v3, v3, v70, v71
	v_max3_f32 v3, v3, v72, v73
	v_max3_f32 v3, v3, v74, v75
	v_max3_f32 v3, v3, v76, v77
	v_max3_f32 v3, v3, v78, v79
	v_max3_f32 v3, v3, v80, v81
	v_max3_f32 v3, v3, v82, v83
	ds_bpermute_b32 v36, v179, v3
	s_waitcnt lgkmcnt(0)
	v_max_f32_e32 v36, v36, v36
	v_max_f32_e32 v3, v3, v36
	v_max3_f32 v132, v218, v3, s46
	v_sub_f32_e32 v3, v218, v132
	v_exp_f32_e32 v170, v3
	s_nop 2
	v_cmp_eq_f32_e32 vcc, 1.0, v170
	s_cmp_eq_u64 vcc, exec
	s_nop 4
	s_cbranch_scc1 .LBB0_1425
	v_mul_f32_e32 v34, v34, v170
	v_mul_f32_e32 v35, v35, v170
	v_mul_f32_e32 v32, v32, v170
	v_mul_f32_e32 v33, v33, v170
	v_mul_f32_e32 v30, v30, v170
	v_mul_f32_e32 v31, v31, v170
	v_mul_f32_e32 v28, v28, v170
	v_mul_f32_e32 v29, v29, v170
	v_mul_f32_e32 v26, v26, v170
	v_mul_f32_e32 v27, v27, v170
	v_mul_f32_e32 v24, v24, v170
	v_mul_f32_e32 v25, v25, v170
	v_mul_f32_e32 v22, v22, v170
	v_mul_f32_e32 v23, v23, v170
	v_mul_f32_e32 v20, v20, v170
	v_mul_f32_e32 v21, v21, v170
	v_mul_f32_e32 v18, v18, v170
	v_mul_f32_e32 v19, v19, v170
	v_mul_f32_e32 v16, v16, v170
	v_mul_f32_e32 v17, v17, v170
	v_mul_f32_e32 v14, v14, v170
	v_mul_f32_e32 v15, v15, v170
	v_mul_f32_e32 v12, v12, v170
	v_mul_f32_e32 v13, v13, v170
	v_mul_f32_e32 v10, v10, v170
	v_mul_f32_e32 v11, v11, v170
	v_mul_f32_e32 v8, v8, v170
	v_mul_f32_e32 v9, v9, v170
	v_mul_f32_e32 v6, v6, v170
	v_mul_f32_e32 v7, v7, v170
	v_mul_f32_e32 v4, v4, v170
	v_mul_f32_e32 v5, v5, v170
.LBB0_1425:
	v_add_u32_e32 v3, v219, v196
	v_sub_f32_e32 v84, v84, v132
	v_sub_f32_e32 v85, v85, v132
	v_sub_f32_e32 v86, v86, v132
	v_sub_f32_e32 v87, v87, v132
	v_sub_f32_e32 v88, v88, v132
	v_sub_f32_e32 v89, v89, v132
	v_sub_f32_e32 v90, v90, v132
	v_sub_f32_e32 v91, v91, v132
	v_add_u32_e32 v171, v3, v190
	v_exp_f32_e32 v84, v84
	v_exp_f32_e32 v85, v85
	v_exp_f32_e32 v86, v86
	v_exp_f32_e32 v87, v87
	v_exp_f32_e32 v88, v88
	v_exp_f32_e32 v89, v89
	v_exp_f32_e32 v90, v90
	v_exp_f32_e32 v91, v91
	v_add_u32_e32 v171, 0x2000, v171
	ds_read2_b64 v[224:227], v171 offset0:128 offset1:130
	ds_read2_b64 v[228:231], v171 offset0:132 offset1:134
	v_add_u32_e32 v3, v3, v191
	v_cvt_pk_bf16_f32 v220, v84, v85
	v_cvt_pk_bf16_f32 v221, v86, v87
	v_cvt_pk_bf16_f32 v222, v88, v89
	v_cvt_pk_bf16_f32 v223, v90, v91
	v_add_u32_e32 v3, 0x2000, v3
	v_sub_f32_e32 v92, v92, v132
	v_sub_f32_e32 v93, v93, v132
	s_waitcnt lgkmcnt(1)
	v_mfma_f32_32x32x16_bf16 v[20:35], v[224:227], v[220:223], v[20:35]
	ds_read2_b64 v[224:227], v3 offset0:128 offset1:130
	ds_read2_b64 v[232:235], v3 offset0:132 offset1:134
	v_add_f32_e64 v94, v94, -v132
	v_add_f32_e64 v95, v95, -v132
	v_add_f32_e64 v96, v96, -v132
	v_add_f32_e64 v97, v97, -v132
	v_sub_f32_e32 v98, v98, v132
	v_sub_f32_e32 v99, v99, v132
	v_exp_f32_e32 v92, v92
	v_exp_f32_e32 v93, v93
	v_exp_f32_e32 v94, v94
	s_waitcnt lgkmcnt(1)
	v_mfma_f32_32x32x16_bf16 v[4:19], v[224:227], v[220:223], v[4:19]
	v_exp_f32_e32 v95, v95
	v_exp_f32_e32 v96, v96
	v_exp_f32_e32 v97, v97
	v_exp_f32_e32 v98, v98
	v_exp_f32_e32 v99, v99
	v_cvt_pk_bf16_f32 v220, v92, v93
	v_cvt_pk_bf16_f32 v221, v94, v95
	v_cvt_pk_bf16_f32 v222, v96, v97
	v_cvt_pk_bf16_f32 v223, v98, v99
	s_nop 1
	v_mfma_f32_32x32x16_bf16 v[20:35], v[228:231], v[220:223], v[20:35]
	s_waitcnt lgkmcnt(0)
	v_mfma_f32_32x32x16_bf16 v[4:19], v[232:235], v[220:223], v[4:19]
	v_add_f32_e64 v74, v74, -v132
	v_add_f32_e64 v75, v75, -v132
	v_add_f32_e64 v68, v68, -v132
	v_add_f32_e64 v69, v69, -v132
	v_add_f32_e64 v70, v70, -v132
	v_add_f32_e64 v71, v71, -v132
	v_sub_f32_e32 v72, v72, v132
	v_sub_f32_e32 v73, v73, v132
	v_exp_f32_e32 v228, v74
	v_exp_f32_e32 v229, v75
	v_sub_f32_e32 v74, v76, v132
	v_sub_f32_e32 v75, v77, v132
	v_exp_f32_e32 v68, v68
	v_exp_f32_e32 v69, v69
	v_exp_f32_e32 v70, v70
	v_exp_f32_e32 v71, v71
	v_exp_f32_e32 v72, v72
	v_exp_f32_e32 v73, v73
	v_exp_f32_e32 v230, v74
	v_exp_f32_e32 v231, v75
	v_sub_f32_e32 v74, v78, v132
	v_sub_f32_e32 v75, v79, v132
	v_cvt_pk_bf16_f32 v76, v72, v73
	v_exp_f32_e32 v232, v74
	v_exp_f32_e32 v233, v75
	v_sub_f32_e32 v74, v80, v132
	v_sub_f32_e32 v75, v81, v132
	ds_read2_b64 v[78:81], v171 offset0:136 offset1:138
	ds_read2_b64 v[220:223], v171 offset0:140 offset1:142
	v_exp_f32_e32 v234, v74
	v_exp_f32_e32 v235, v75
	v_sub_f32_e32 v74, v82, v132
	v_sub_f32_e32 v75, v83, v132
	v_cvt_pk_bf16_f32 v77, v228, v229
	v_exp_f32_e32 v82, v74
	v_exp_f32_e32 v83, v75
	v_cvt_pk_bf16_f32 v74, v68, v69
	v_cvt_pk_bf16_f32 v75, v70, v71
	s_mov_b64 s[26:27], 0
	s_waitcnt lgkmcnt(1)
	v_mfma_f32_32x32x16_bf16 v[20:35], v[78:81], v[74:77], v[20:35]
	ds_read2_b64 v[78:81], v3 offset0:136 offset1:138
	ds_read2_b64 v[224:227], v3 offset0:140 offset1:142
	s_waitcnt lgkmcnt(1)
	v_mfma_f32_32x32x16_bf16 v[4:19], v[78:81], v[74:77], v[4:19]
	v_cvt_pk_bf16_f32 v74, v230, v231
	v_cvt_pk_bf16_f32 v75, v232, v233
	v_cvt_pk_bf16_f32 v76, v234, v235
	v_cvt_pk_bf16_f32 v77, v82, v83
	s_nop 1
	v_mfma_f32_32x32x16_bf16 v[20:35], v[220:223], v[74:77], v[20:35]
	s_waitcnt lgkmcnt(0)
	v_mfma_f32_32x32x16_bf16 v[4:19], v[224:227], v[74:77], v[4:19]
	v_add_f32_e64 v74, v84, 0
	v_add_f32_e64 v75, v85, 0
	v_add_f32_e64 v74, v86, v74
	v_add_f32_e64 v75, v87, v75
	v_add_f32_e64 v74, v88, v74
	v_add_f32_e64 v75, v89, v75
	v_add_f32_e32 v74, v90, v74
	v_add_f32_e32 v75, v91, v75
	s_nop 0
	v_add_f32_e32 v74, v92, v74
	v_add_f32_e32 v75, v93, v75
	s_nop 0
	v_add_f32_e32 v74, v94, v74
	v_add_f32_e32 v75, v95, v75
	s_nop 0
	v_add_f32_e32 v74, v96, v74
	v_add_f32_e32 v75, v97, v75
	s_nop 0
	v_add_f32_e32 v74, v98, v74
	v_add_f32_e32 v75, v99, v75
	s_nop 0
	v_add_f32_e32 v68, v68, v74
	v_add_f32_e32 v69, v69, v75
	s_nop 0
	v_add_f32_e32 v68, v70, v68
	v_add_f32_e32 v69, v71, v69
	s_nop 0
	v_add_f32_e32 v68, v72, v68
	v_add_f32_e32 v69, v73, v69
	s_nop 0
	v_add_f32_e32 v68, v228, v68
	v_add_f32_e32 v69, v229, v69
	s_nop 0
	v_add_f32_e32 v68, v230, v68
	v_add_f32_e32 v69, v231, v69
	s_nop 0
	v_add_f32_e32 v68, v232, v68
	v_add_f32_e32 v69, v233, v69
	s_nop 0
	v_add_f32_e32 v68, v234, v68
	v_add_f32_e32 v69, v235, v69
	s_nop 0
	v_add_f32_e32 v68, v82, v68
	v_add_f32_e32 v69, v83, v69
	s_nop 0
	v_add_f32_e32 v3, v68, v69
	ds_bpermute_b32 v68, v179, v3
	s_waitcnt lgkmcnt(0)
	v_add_f32_e32 v3, v3, v68
	v_fmac_f32_e32 v3, v217, v170

.LBB0_1427:
	v_sub_u32_e32 v68, v161, v165
	s_cmp_gt_i32 s42, s76
	v_cvt_f32_i32_e32 v220, v68
	s_cselect_b64 s[2:3], -1, 0
	s_and_b64 s[8:9], s[24:25], s[2:3]
	v_add_u32_e32 v69, s38, v176
	s_mov_b64 s[2:3], -1
	s_andn2_b64 vcc, exec, s[8:9]
	v_add_u32_e32 v219, v69, v177
	v_add_u32_e32 v165, v69, v178
	s_cbranch_vccz .LBB0_1431
	v_mov_b32_e32 v3, v157
	ds_read_b128 v[52:55], v219
	ds_read_b128 v[56:59], v219 offset:32
	v_mul_f32_e64 v66, v220, -v3
	v_mov_b32_e32 v78, v3
	v_fma_f32 v38, 0, v3, v66
	v_fmamk_f32 v42, v3, 0x41000000, v66
	v_fmamk_f32 v46, v3, 0x41800000, v66
	v_fmamk_f32 v50, v3, 0x41c00000, v66
	v_add_f32_e32 v36, v2, v38
	v_add_f32_e32 v37, v3, v38
	v_fma_f32 v39, v78, s65, v38
	v_fma_f32 v38, v78, s64, v38
	v_add_f32_e32 v40, v2, v42
	v_add_f32_e32 v41, v3, v42
	v_fma_f32 v43, v78, s65, v42
	v_fma_f32 v42, v78, s64, v42
	v_add_f32_e32 v44, v2, v46
	v_add_f32_e32 v45, v3, v46
	v_fma_f32 v47, v78, s65, v46
	v_fma_f32 v46, v78, s64, v46
	v_add_f32_e32 v48, v2, v50
	v_add_f32_e32 v49, v3, v50
	v_fma_f32 v51, v78, s65, v50
	v_fma_f32 v50, v78, s64, v50
	v_fmamk_f32 v60, v3, 0x42200000, v66
	v_fmamk_f32 v62, v3, 0x42400000, v66
	s_waitcnt lgkmcnt(1)
	v_mfma_f32_32x32x16_bf16 v[36:51], v[52:55], v[100:103], v[36:51]
	v_cmp_gt_u32_e32 vcc, s47, v68
	s_waitcnt lgkmcnt(0)
	v_mfma_f32_32x32x16_bf16 v[36:51], v[56:59], v[104:107], v[36:51]
	ds_read_b128 v[52:55], v219 offset:64
	ds_read_b128 v[56:59], v219 offset:96
	ds_read_b128 v[70:73], v165
	ds_read_b128 v[74:77], v165 offset:32
	s_waitcnt lgkmcnt(3)
	v_mfma_f32_32x32x16_bf16 v[36:51], v[52:55], v[108:111], v[36:51]
	v_fmamk_f32 v54, v3, 0x42000000, v66
	v_fmac_f32_e32 v66, 0x42600000, v3
	v_add_f32_e64 v52, v2, v54
	v_add_f32_e64 v53, v3, v54
	v_fma_f32 v55, v78, s65, v54
	v_fma_f32 v54, v78, s64, v54
	v_add_f32_e32 v64, v2, v66
	v_add_f32_e32 v65, v3, v66
	v_fma_f32 v67, v78, s65, v66
	v_fma_f32 v66, v78, s64, v66
	s_waitcnt lgkmcnt(2)
	v_mfma_f32_32x32x16_bf16 v[36:51], v[56:59], v[112:115], v[36:51]
	v_add_f32_e64 v56, v2, v60
	v_add_f32_e64 v57, v3, v60
	v_fma_f32 v58, v78, s64, v60
	v_fma_f32 v59, v78, s65, v60
	v_add_f32_e64 v60, v2, v62
	v_add_f32_e64 v61, v3, v62
	v_fma_f32 v63, v78, s65, v62
	v_fma_f32 v62, v78, s64, v62
	v_add_u32_e32 v3, -1, v68
	s_nop 3
	v_cndmask_b32_e32 v88, v214, v36, vcc
	s_waitcnt lgkmcnt(1)
	v_mfma_f32_32x32x16_bf16 v[52:67], v[70:73], v[100:103], v[52:67]
	ds_read_b128 v[70:73], v165 offset:64
	ds_read_b128 v[78:81], v165 offset:96
	v_cmp_gt_u32_e32 vcc, s47, v3
	v_add_u32_e32 v36, -2, v68
	s_nop 0
	v_cndmask_b32_e32 v89, v214, v37, vcc
	v_cmp_gt_u32_e32 vcc, s47, v36
	v_add_u32_e32 v36, -3, v68
	s_waitcnt lgkmcnt(2)
	v_mfma_f32_32x32x16_bf16 v[52:67], v[74:77], v[104:107], v[52:67]
	v_cndmask_b32_e32 v94, v214, v38, vcc
	v_cmp_gt_u32_e32 vcc, s47, v36
	v_add_u32_e32 v36, -8, v68
	v_max3_f32 v3, v88, s97, v89
	v_cndmask_b32_e32 v95, v214, v39, vcc
	v_cmp_gt_u32_e32 vcc, s47, v36
	v_add_u32_e32 v36, -9, v68
	s_waitcnt lgkmcnt(1)
	v_mfma_f32_32x32x16_bf16 v[52:67], v[70:73], v[108:111], v[52:67]
	v_cndmask_b32_e32 v96, v214, v40, vcc
	v_cmp_gt_u32_e32 vcc, s47, v36
	v_add_u32_e32 v36, -10, v68
	v_max3_f32 v3, v3, v94, v95
	v_cndmask_b32_e32 v97, v214, v41, vcc
	v_cmp_gt_u32_e32 vcc, s47, v36
	v_add_u32_e32 v36, -11, v68
	s_waitcnt lgkmcnt(0)
	v_mfma_f32_32x32x16_bf16 v[52:67], v[78:81], v[112:115], v[52:67]
	v_cndmask_b32_e32 v98, v214, v42, vcc
	v_cmp_gt_u32_e32 vcc, s47, v36
	v_add_u32_e32 v36, -16, v68
	v_max3_f32 v3, v3, v96, v97
	v_cndmask_b32_e32 v99, v214, v43, vcc
	v_cmp_gt_u32_e32 vcc, s47, v36
	v_subrev_u32_e32 v36, 17, v68
	v_max3_f32 v3, v3, v98, v99
	v_cndmask_b32_e32 v170, v214, v44, vcc
	v_cmp_gt_u32_e32 vcc, s47, v36
	v_subrev_u32_e32 v36, 18, v68
	s_nop 0
	v_cndmask_b32_e32 v171, v214, v45, vcc
	v_cmp_gt_u32_e32 vcc, s47, v36
	v_subrev_u32_e32 v36, 19, v68
	v_max3_f32 v3, v3, v170, v171
	v_cndmask_b32_e32 v90, v214, v46, vcc
	v_cmp_gt_u32_e32 vcc, s47, v36
	v_subrev_u32_e32 v36, 24, v68
	s_nop 0
	v_cndmask_b32_e32 v91, v214, v47, vcc
	v_cmp_gt_u32_e32 vcc, s47, v36
	v_subrev_u32_e32 v36, 25, v68
	v_max3_f32 v3, v3, v90, v91
	v_cndmask_b32_e32 v92, v214, v48, vcc
	v_cmp_gt_u32_e32 vcc, s47, v36
	v_subrev_u32_e32 v36, 26, v68
	s_nop 0
	v_cndmask_b32_e32 v93, v214, v49, vcc
	v_cmp_gt_u32_e32 vcc, s47, v36
	v_subrev_u32_e32 v36, 27, v68
	v_max3_f32 v3, v3, v92, v93
	v_cndmask_b32_e32 v86, v214, v50, vcc
	v_cmp_gt_u32_e32 vcc, s47, v36
	v_subrev_u32_e32 v36, 32, v68
	s_nop 0
	v_cndmask_b32_e32 v87, v214, v51, vcc
	v_cmp_gt_u32_e32 vcc, s47, v36
	v_subrev_u32_e32 v36, 33, v68
	v_max3_f32 v3, v3, v86, v87
	v_cndmask_b32_e32 v76, v214, v52, vcc
	v_cmp_gt_u32_e32 vcc, s47, v36
	v_subrev_u32_e32 v36, 34, v68
	s_nop 0
	v_cndmask_b32_e32 v77, v214, v53, vcc
	v_cmp_gt_u32_e32 vcc, s47, v36
	v_subrev_u32_e32 v36, 35, v68
	v_max3_f32 v3, v3, v76, v77
	v_cndmask_b32_e32 v78, v214, v54, vcc
	v_cmp_gt_u32_e32 vcc, s47, v36
	v_subrev_u32_e32 v36, 40, v68
	s_nop 0
	v_cndmask_b32_e32 v79, v214, v55, vcc
	v_cmp_gt_u32_e32 vcc, s47, v36
	v_subrev_u32_e32 v36, 41, v68
	v_max3_f32 v3, v3, v78, v79
	v_cndmask_b32_e32 v80, v214, v56, vcc
	v_cmp_gt_u32_e32 vcc, s47, v36
	v_subrev_u32_e32 v36, 42, v68
	s_nop 0
	v_cndmask_b32_e32 v81, v214, v57, vcc
	v_cmp_gt_u32_e32 vcc, s47, v36
	v_subrev_u32_e32 v36, 43, v68
	v_max3_f32 v3, v3, v80, v81
	v_cndmask_b32_e32 v82, v214, v58, vcc
	v_cmp_gt_u32_e32 vcc, s47, v36
	v_subrev_u32_e32 v36, 48, v68
	s_nop 0
	v_cndmask_b32_e32 v83, v214, v59, vcc
	v_cmp_gt_u32_e32 vcc, s47, v36
	v_subrev_u32_e32 v36, 49, v68
	v_max3_f32 v3, v3, v82, v83
	v_cndmask_b32_e32 v84, v214, v60, vcc
	v_cmp_gt_u32_e32 vcc, s47, v36
	v_subrev_u32_e32 v36, 50, v68
	s_nop 0
	v_cndmask_b32_e32 v85, v214, v61, vcc
	v_cmp_gt_u32_e32 vcc, s47, v36
	v_subrev_u32_e32 v36, 51, v68
	v_max3_f32 v3, v3, v84, v85
	v_cndmask_b32_e32 v74, v214, v62, vcc
	v_cmp_gt_u32_e32 vcc, s47, v36
	v_subrev_u32_e32 v36, 56, v68
	s_nop 0
	v_cndmask_b32_e32 v75, v214, v63, vcc
	v_cmp_gt_u32_e32 vcc, s47, v36
	v_subrev_u32_e32 v36, 57, v68
	v_max3_f32 v3, v3, v74, v75
	v_cndmask_b32_e32 v70, v214, v64, vcc
	v_cmp_gt_u32_e32 vcc, s47, v36
	v_subrev_u32_e32 v36, 58, v68
	s_nop 0
	v_cndmask_b32_e32 v71, v214, v65, vcc
	v_cmp_gt_u32_e32 vcc, s47, v36
	v_subrev_u32_e32 v36, 59, v68
	v_max3_f32 v3, v3, v70, v71
	v_cndmask_b32_e32 v72, v214, v66, vcc
	v_cmp_gt_u32_e32 vcc, s47, v36
	s_nop 1
	v_cndmask_b32_e32 v73, v214, v67, vcc
	v_max3_f32 v3, v3, v72, v73
	ds_bpermute_b32 v36, v179, v3
	s_nop 3
	s_waitcnt lgkmcnt(0)
	v_max_f32_e32 v36, v36, v36
	v_max_f32_e32 v3, v3, v36
	v_max3_f32 v132, v218, v3, s46
	v_sub_f32_e32 v3, v218, v132
	v_exp_f32_e32 v68, v3
	s_nop 2
	v_cmp_eq_f32_e32 vcc, 1.0, v68
	s_cmp_eq_u64 vcc, exec
	s_nop 8
	s_cbranch_scc1 .LBB0_1430
	v_mul_f32_e32 v34, v34, v68
	v_mul_f32_e32 v35, v35, v68
	v_mul_f32_e32 v32, v32, v68
	v_mul_f32_e32 v33, v33, v68
	v_mul_f32_e32 v30, v30, v68
	v_mul_f32_e32 v31, v31, v68
	v_mul_f32_e32 v28, v28, v68
	v_mul_f32_e32 v29, v29, v68
	v_mul_f32_e32 v26, v26, v68
	v_mul_f32_e32 v27, v27, v68
	v_mul_f32_e32 v24, v24, v68
	v_mul_f32_e32 v25, v25, v68
	v_mul_f32_e32 v22, v22, v68
	v_mul_f32_e32 v23, v23, v68
	v_mul_f32_e32 v20, v20, v68
	v_mul_f32_e32 v21, v21, v68
	v_mul_f32_e32 v18, v18, v68
	v_mul_f32_e32 v19, v19, v68
	v_mul_f32_e32 v16, v16, v68
	v_mul_f32_e32 v17, v17, v68
	v_mul_f32_e32 v14, v14, v68
	v_mul_f32_e32 v15, v15, v68
	v_mul_f32_e32 v12, v12, v68
	v_mul_f32_e32 v13, v13, v68
	v_mul_f32_e32 v10, v10, v68
	v_mul_f32_e32 v11, v11, v68
	v_mul_f32_e32 v8, v8, v68
	v_mul_f32_e32 v9, v9, v68
	v_mul_f32_e32 v6, v6, v68
	v_mul_f32_e32 v7, v7, v68
	v_mul_f32_e32 v4, v4, v68
	v_mul_f32_e32 v5, v5, v68
.LBB0_1430:
	v_sub_f32_e32 v94, v94, v132
	v_sub_f32_e32 v95, v95, v132
	v_lshl_add_u32 v3, v136, 1, s38
	v_exp_f32_e32 v230, v94
	v_exp_f32_e32 v231, v95
	v_sub_f32_e32 v94, v96, v132
	v_sub_f32_e32 v95, v97, v132
	v_sub_f32_e32 v88, v88, v132
	v_sub_f32_e32 v89, v89, v132
	v_exp_f32_e32 v232, v94
	v_exp_f32_e32 v233, v95
	v_sub_f32_e32 v94, v98, v132
	v_sub_f32_e32 v95, v99, v132
	v_exp_f32_e32 v88, v88
	v_exp_f32_e32 v98, v94
	v_add_u32_e32 v94, v3, v190
	v_add_u32_e32 v186, 0x2000, v94
	v_exp_f32_e32 v99, v95
	ds_read2_b64 v[94:97], v186 offset0:128 offset1:130
	v_add_u32_e32 v3, v3, v191
	v_add_u32_e32 v3, 0x2000, v3
	ds_read2_b64 v[226:229], v3 offset0:128 offset1:130
	v_exp_f32_e32 v89, v89
	v_sub_f32_e32 v90, v90, v132
	v_sub_f32_e32 v91, v91, v132
	v_cvt_pk_bf16_f32 v223, v230, v231
	v_exp_f32_e32 v234, v90
	v_exp_f32_e32 v235, v91
	v_sub_f32_e32 v90, v92, v132
	v_sub_f32_e32 v91, v93, v132
	v_cvt_pk_bf16_f32 v222, v88, v89
	v_cvt_pk_bf16_f32 v224, v232, v233
	v_cvt_pk_bf16_f32 v225, v98, v99
	v_exp_f32_e32 v236, v90
	v_exp_f32_e32 v237, v91
	ds_read2_b64 v[90:93], v186 offset0:132 offset1:134
	s_waitcnt lgkmcnt(2)
	v_mfma_f32_32x32x16_bf16 v[20:35], v[94:97], v[222:225], v[20:35]
	v_add_f32_e64 v170, v170, -v132
	v_add_f32_e64 v171, v171, -v132
	v_add_f32_e64 v86, v86, -v132
	v_add_f32_e64 v87, v87, -v132
	v_exp_f32_e32 v170, v170
	v_exp_f32_e32 v171, v171
	v_cvt_pk_bf16_f32 v95, v234, v235
	v_cvt_pk_bf16_f32 v96, v236, v237
	v_cvt_pk_bf16_f32 v94, v170, v171
	s_waitcnt lgkmcnt(1)
	v_mfma_f32_32x32x16_bf16 v[4:19], v[226:229], v[222:225], v[4:19]
	v_exp_f32_e32 v222, v86
	v_exp_f32_e32 v223, v87
	s_nop 0
	v_cvt_pk_bf16_f32 v97, v222, v223
	s_waitcnt lgkmcnt(0)
	s_nop 0
	v_mfma_f32_32x32x16_bf16 v[20:35], v[90:93], v[94:97], v[20:35]
	ds_read2_b64 v[90:93], v3 offset0:132 offset1:134
	s_waitcnt lgkmcnt(0)
	v_mfma_f32_32x32x16_bf16 v[4:19], v[90:93], v[94:97], v[4:19]
	v_add_f32_e64 v76, v76, -v132
	v_add_f32_e64 v77, v77, -v132
	v_add_f32_e64 v74, v74, -v132
	v_add_f32_e64 v75, v75, -v132
	v_exp_f32_e32 v90, v76
	v_exp_f32_e32 v91, v77
	v_sub_f32_e32 v76, v78, v132
	v_sub_f32_e32 v77, v79, v132
	v_sub_f32_e32 v70, v70, v132
	v_sub_f32_e32 v71, v71, v132
	v_exp_f32_e32 v92, v76
	v_exp_f32_e32 v93, v77
	v_sub_f32_e32 v76, v80, v132
	v_sub_f32_e32 v77, v81, v132
	v_sub_f32_e32 v80, v84, v132
	v_sub_f32_e32 v81, v85, v132
	v_exp_f32_e32 v94, v76
	v_exp_f32_e32 v95, v77
	v_sub_f32_e32 v76, v82, v132
	v_sub_f32_e32 v77, v83, v132
	ds_read2_b64 v[84:87], v3 offset0:136 offset1:138
	v_exp_f32_e32 v96, v76
	v_exp_f32_e32 v97, v77
	ds_read2_b64 v[76:79], v186 offset0:136 offset1:138
	v_exp_f32_e32 v224, v80
	v_exp_f32_e32 v225, v81
	v_cvt_pk_bf16_f32 v80, v90, v91
	v_cvt_pk_bf16_f32 v81, v92, v93
	v_cvt_pk_bf16_f32 v82, v94, v95
	v_cvt_pk_bf16_f32 v83, v96, v97
	v_exp_f32_e32 v226, v74
	v_exp_f32_e32 v227, v75
	v_exp_f32_e32 v228, v70
	v_exp_f32_e32 v229, v71
	v_sub_f32_e32 v74, v72, v132
	v_sub_f32_e32 v75, v73, v132
	ds_read2_b64 v[70:73], v186 offset0:140 offset1:142
	s_waitcnt lgkmcnt(1)
	v_mfma_f32_32x32x16_bf16 v[20:35], v[76:79], v[80:83], v[20:35]
	v_cvt_pk_bf16_f32 v78, v224, v225
	v_cvt_pk_bf16_f32 v79, v226, v227
	s_mov_b64 s[2:3], 0
	v_mfma_f32_32x32x16_bf16 v[4:19], v[84:87], v[80:83], v[4:19]
	v_exp_f32_e32 v82, v74
	v_exp_f32_e32 v83, v75
	v_cvt_pk_bf16_f32 v80, v228, v229
	ds_read2_b64 v[74:77], v3 offset0:140 offset1:142
	v_cvt_pk_bf16_f32 v81, v82, v83
	s_waitcnt lgkmcnt(1)
	s_nop 0
	v_mfma_f32_32x32x16_bf16 v[20:35], v[70:73], v[78:81], v[20:35]
	v_add_f32_e64 v70, v88, 0
	v_add_f32_e64 v71, v89, 0
	v_add_f32_e64 v70, v230, v70
	v_add_f32_e64 v71, v231, v71
	v_add_f32_e64 v70, v232, v70
	v_add_f32_e64 v71, v233, v71
	v_add_f32_e32 v70, v98, v70
	v_add_f32_e32 v71, v99, v71
	s_waitcnt lgkmcnt(0)
	v_mfma_f32_32x32x16_bf16 v[4:19], v[74:77], v[78:81], v[4:19]
	v_add_f32_e64 v70, v170, v70
	v_add_f32_e64 v71, v171, v71
	v_add_f32_e64 v70, v234, v70
	v_add_f32_e64 v71, v235, v71
	v_add_f32_e64 v70, v236, v70
	v_add_f32_e64 v71, v237, v71
	v_add_f32_e32 v70, v222, v70
	v_add_f32_e32 v71, v223, v71
	s_nop 0
	v_add_f32_e32 v70, v90, v70
	v_add_f32_e32 v71, v91, v71
	s_nop 0
	v_add_f32_e32 v70, v92, v70
	v_add_f32_e32 v71, v93, v71
	s_nop 0
	v_add_f32_e32 v70, v94, v70
	v_add_f32_e32 v71, v95, v71
	s_nop 0
	v_add_f32_e32 v70, v96, v70
	v_add_f32_e32 v71, v97, v71
	s_nop 0
	v_add_f32_e32 v70, v224, v70
	v_add_f32_e32 v71, v225, v71
	s_nop 0
	v_add_f32_e32 v70, v226, v70
	v_add_f32_e32 v71, v227, v71
	s_nop 0
	v_add_f32_e32 v70, v228, v70
	v_add_f32_e32 v71, v229, v71
	s_nop 0
	v_add_f32_e32 v70, v82, v70
	v_add_f32_e32 v71, v83, v71
	s_nop 0
	v_add_f32_e32 v3, v70, v71
	ds_bpermute_b32 v70, v179, v3
	s_waitcnt lgkmcnt(0)
	v_add_f32_e32 v3, v3, v70
	v_fmac_f32_e32 v3, v217, v68

.LBB0_1434:
	v_add_u32_e32 v3, v69, v196
	v_sub_f32_e32 v52, v52, v132
	v_sub_f32_e32 v53, v53, v132
	v_sub_f32_e32 v54, v54, v132
	v_sub_f32_e32 v55, v55, v132
	v_sub_f32_e32 v56, v56, v132
	v_sub_f32_e32 v57, v57, v132
	v_sub_f32_e32 v58, v58, v132
	v_sub_f32_e32 v59, v59, v132
	v_add_u32_e32 v69, v3, v190
	v_exp_f32_e32 v52, v52
	v_exp_f32_e32 v53, v53
	v_exp_f32_e32 v54, v54
	v_exp_f32_e32 v55, v55
	v_exp_f32_e32 v56, v56
	v_exp_f32_e32 v57, v57
	v_exp_f32_e32 v58, v58
	v_exp_f32_e32 v59, v59
	v_add_u32_e32 v69, 0x2000, v69
	ds_read2_b64 v[74:77], v69 offset0:128 offset1:130
	ds_read2_b64 v[78:81], v69 offset0:132 offset1:134
	v_add_u32_e32 v3, v3, v191
	v_cvt_pk_bf16_f32 v70, v52, v53
	v_cvt_pk_bf16_f32 v71, v54, v55
	v_cvt_pk_bf16_f32 v72, v56, v57
	v_cvt_pk_bf16_f32 v73, v58, v59
	v_add_u32_e32 v3, 0x2000, v3
	v_sub_f32_e32 v60, v60, v132
	v_sub_f32_e32 v61, v61, v132
	s_waitcnt lgkmcnt(1)
	v_mfma_f32_32x32x16_bf16 v[20:35], v[74:77], v[70:73], v[20:35]
	ds_read2_b64 v[74:77], v3 offset0:128 offset1:130
	ds_read2_b64 v[82:85], v3 offset0:132 offset1:134
	v_add_f32_e64 v62, v62, -v132
	v_add_f32_e64 v63, v63, -v132
	v_add_f32_e64 v64, v64, -v132
	v_add_f32_e64 v65, v65, -v132
	v_sub_f32_e32 v66, v66, v132
	v_sub_f32_e32 v67, v67, v132
	v_exp_f32_e32 v60, v60
	v_exp_f32_e32 v61, v61
	v_exp_f32_e32 v62, v62
	s_waitcnt lgkmcnt(1)
	v_mfma_f32_32x32x16_bf16 v[4:19], v[74:77], v[70:73], v[4:19]
	v_exp_f32_e32 v63, v63
	v_exp_f32_e32 v64, v64
	v_exp_f32_e32 v65, v65
	v_exp_f32_e32 v66, v66
	v_exp_f32_e32 v67, v67
	v_cvt_pk_bf16_f32 v70, v60, v61
	v_cvt_pk_bf16_f32 v71, v62, v63
	v_cvt_pk_bf16_f32 v72, v64, v65
	v_cvt_pk_bf16_f32 v73, v66, v67
	s_nop 1
	v_mfma_f32_32x32x16_bf16 v[20:35], v[78:81], v[70:73], v[20:35]
	s_waitcnt lgkmcnt(0)
	v_mfma_f32_32x32x16_bf16 v[4:19], v[82:85], v[70:73], v[4:19]
	v_add_f32_e64 v42, v42, -v132
	v_add_f32_e64 v43, v43, -v132
	v_add_f32_e64 v36, v36, -v132
	v_add_f32_e64 v37, v37, -v132
	v_add_f32_e64 v38, v38, -v132
	v_add_f32_e64 v39, v39, -v132
	v_sub_f32_e32 v40, v40, v132
	v_sub_f32_e32 v41, v41, v132
	v_exp_f32_e32 v78, v42
	v_exp_f32_e32 v79, v43
	v_sub_f32_e32 v42, v44, v132
	v_sub_f32_e32 v43, v45, v132
	v_exp_f32_e32 v36, v36
	v_exp_f32_e32 v37, v37
	v_exp_f32_e32 v38, v38
	v_exp_f32_e32 v39, v39
	v_exp_f32_e32 v40, v40
	v_exp_f32_e32 v41, v41
	v_exp_f32_e32 v80, v42
	v_exp_f32_e32 v81, v43
	v_sub_f32_e32 v42, v46, v132
	v_sub_f32_e32 v43, v47, v132
	v_cvt_pk_bf16_f32 v44, v40, v41
	v_exp_f32_e32 v82, v42
	v_exp_f32_e32 v83, v43
	v_sub_f32_e32 v42, v48, v132
	v_sub_f32_e32 v43, v49, v132
	ds_read2_b64 v[46:49], v69 offset0:136 offset1:138
	ds_read2_b64 v[70:73], v69 offset0:140 offset1:142
	v_exp_f32_e32 v84, v42
	v_exp_f32_e32 v85, v43
	v_sub_f32_e32 v42, v50, v132
	v_sub_f32_e32 v43, v51, v132
	v_cvt_pk_bf16_f32 v45, v78, v79
	v_exp_f32_e32 v50, v42
	v_exp_f32_e32 v51, v43
	v_cvt_pk_bf16_f32 v42, v36, v37
	v_cvt_pk_bf16_f32 v43, v38, v39
	s_waitcnt lgkmcnt(1)
	s_nop 0
	v_mfma_f32_32x32x16_bf16 v[20:35], v[46:49], v[42:45], v[20:35]
	ds_read2_b64 v[46:49], v3 offset0:136 offset1:138
	ds_read2_b64 v[74:77], v3 offset0:140 offset1:142
	s_waitcnt lgkmcnt(1)
	v_mfma_f32_32x32x16_bf16 v[4:19], v[46:49], v[42:45], v[4:19]
	v_cvt_pk_bf16_f32 v42, v80, v81
	v_cvt_pk_bf16_f32 v43, v82, v83
	v_cvt_pk_bf16_f32 v44, v84, v85
	v_cvt_pk_bf16_f32 v45, v50, v51
	s_nop 1
	v_mfma_f32_32x32x16_bf16 v[20:35], v[70:73], v[42:45], v[20:35]
	s_waitcnt lgkmcnt(0)
	v_mfma_f32_32x32x16_bf16 v[4:19], v[74:77], v[42:45], v[4:19]
	v_add_f32_e64 v42, v52, 0
	v_add_f32_e64 v43, v53, 0
	v_add_f32_e64 v42, v54, v42
	v_add_f32_e64 v43, v55, v43
	v_add_f32_e64 v42, v56, v42
	v_add_f32_e64 v43, v57, v43
	v_add_f32_e32 v42, v58, v42
	v_add_f32_e32 v43, v59, v43
	s_nop 0
	v_add_f32_e32 v42, v60, v42
	v_add_f32_e32 v43, v61, v43
	s_nop 0
	v_add_f32_e32 v42, v62, v42
	v_add_f32_e32 v43, v63, v43
	s_nop 0
	v_add_f32_e32 v42, v64, v42
	v_add_f32_e32 v43, v65, v43
	s_nop 0
	v_add_f32_e32 v42, v66, v42
	v_add_f32_e32 v43, v67, v43
	s_nop 0
	v_add_f32_e32 v36, v36, v42
	v_add_f32_e32 v37, v37, v43
	s_nop 0
	v_add_f32_e32 v36, v38, v36
	v_add_f32_e32 v37, v39, v37
	s_nop 0
	v_add_f32_e32 v36, v40, v36
	v_add_f32_e32 v37, v41, v37
	s_nop 0
	v_add_f32_e32 v36, v78, v36
	v_add_f32_e32 v37, v79, v37
	s_nop 0
	v_add_f32_e32 v36, v80, v36
	v_add_f32_e32 v37, v81, v37
	s_nop 0
	v_add_f32_e32 v36, v82, v36
	v_add_f32_e32 v37, v83, v37
	s_nop 0
	v_add_f32_e32 v36, v84, v36
	v_add_f32_e32 v37, v85, v37
	s_nop 0
	v_add_f32_e32 v36, v50, v36
	v_add_f32_e32 v37, v51, v37
	s_nop 0
	v_add_f32_e32 v3, v36, v37
	ds_bpermute_b32 v36, v179, v3
	s_waitcnt lgkmcnt(0)
	v_add_f32_e32 v3, v3, v36
	s_nop 0
	v_fmac_f32_e32 v3, v217, v68
	s_nop 6
	s_branch .LBB0_1442

.LBB0_1443:
	s_and_b64 vcc, exec, s[0:1]
	s_cbranch_vccnz .LBB0_1465
	v_lshrrev_b32_e32 v3, s39, v159
	v_and_b32_e32 v3, 1, v3
	v_cmp_eq_u32_e64 s[0:1], 1, v3
	s_or_b64 s[2:3], s[28:29], s[0:1]
	v_cndmask_b32_e64 v3, 0, 1, s[2:3]
	v_cmp_ne_u32_e32 vcc, 0, v3
	s_cbranch_vccz .LBB0_1465
	s_cmp_lt_i32 s39, s48
	s_cselect_b64 s[2:3], -1, 0
	s_cmp_ge_i32 s39, s48
	v_add_u32_e32 v165, s38, v176
	s_cselect_b64 s[26:27], -1, 0
	s_mov_b64 s[24:25], -1
	s_and_b64 vcc, exec, s[20:21]
	v_lshl_or_b32 v221, s39, 6, v136
	v_add_u32_e32 v220, v165, v177
	v_add_u32_e32 v219, v165, v178
	s_cbranch_vccz .LBB0_1454
	v_sub_u32_e32 v68, v161, v221
	v_cvt_f32_i32_e32 v69, v68
	s_and_b64 vcc, exec, s[26:27]
	s_cbranch_vccz .LBB0_1450
	v_mov_b32_e32 v3, v157
	ds_read_b128 v[52:55], v220 offset:17920
	ds_read_b128 v[56:59], v220 offset:17952
	v_mul_f32_e64 v36, v69, -v3
	v_cndmask_b32_e64 v66, v214, v36, s[0:1]
	v_mov_b32_e32 v74, v3
	v_fma_f32 v38, 0, v3, v66
	v_fmamk_f32 v42, v3, 0x41000000, v66
	v_fmamk_f32 v46, v3, 0x41800000, v66
	v_fmamk_f32 v50, v3, 0x41c00000, v66
	v_add_f32_e32 v36, v2, v38
	v_add_f32_e32 v37, v3, v38
	v_fma_f32 v39, v74, s65, v38
	v_fma_f32 v38, v74, s64, v38
	v_add_f32_e32 v40, v2, v42
	v_add_f32_e32 v41, v3, v42
	v_fma_f32 v43, v74, s65, v42
	v_fma_f32 v42, v74, s64, v42
	v_add_f32_e32 v44, v2, v46
	v_add_f32_e32 v45, v3, v46
	v_fma_f32 v47, v74, s65, v46
	v_fma_f32 v46, v74, s64, v46
	v_add_f32_e32 v48, v2, v50
	v_add_f32_e32 v49, v3, v50
	v_fma_f32 v51, v74, s65, v50
	v_fma_f32 v50, v74, s64, v50
	v_fmamk_f32 v62, v3, 0x42200000, v66
	v_fmamk_f32 v64, v3, 0x42400000, v66
	s_waitcnt lgkmcnt(1)
	v_mfma_f32_32x32x16_bf16 v[36:51], v[52:55], v[100:103], v[36:51]
	v_cmp_lt_i32_e32 vcc, -1, v68
	s_waitcnt lgkmcnt(0)
	v_mfma_f32_32x32x16_bf16 v[36:51], v[56:59], v[104:107], v[36:51]
	ds_read_b128 v[52:55], v220 offset:17984
	ds_read_b128 v[58:61], v220 offset:18016
	ds_read_b128 v[70:73], v219 offset:17920
	v_add_f32_e64 v56, v2, v62
	v_add_f32_e64 v57, v3, v62
	s_waitcnt lgkmcnt(2)
	v_mfma_f32_32x32x16_bf16 v[36:51], v[52:55], v[108:111], v[36:51]
	v_fmamk_f32 v54, v3, 0x42000000, v66
	v_fmac_f32_e32 v66, 0x42600000, v3
	v_add_f32_e64 v52, v2, v54
	v_add_f32_e64 v53, v3, v54
	v_fma_f32 v55, v74, s65, v54
	v_fma_f32 v54, v74, s64, v54
	s_waitcnt lgkmcnt(1)
	v_mfma_f32_32x32x16_bf16 v[36:51], v[58:61], v[112:115], v[36:51]
	v_fma_f32 v58, v74, s64, v62
	v_fma_f32 v59, v74, s65, v62
	v_add_f32_e64 v60, v2, v64
	v_add_f32_e64 v61, v3, v64
	v_fma_f32 v62, v74, s64, v64
	v_fma_f32 v63, v74, s65, v64
	v_add_f32_e32 v64, v2, v66
	v_add_f32_e32 v65, v3, v66
	v_fma_f32 v67, v74, s65, v66
	v_fma_f32 v66, v74, s64, v66
	ds_read_b128 v[74:77], v219 offset:17952
	s_nop 2
	v_cndmask_b32_e32 v86, v214, v36, vcc
	s_waitcnt lgkmcnt(1)
	v_mfma_f32_32x32x16_bf16 v[52:67], v[70:73], v[100:103], v[52:67]
	ds_read_b128 v[70:73], v219 offset:17984
	ds_read_b128 v[78:81], v219 offset:18016
	v_cmp_lt_i32_e32 vcc, 0, v68
	s_nop 1
	v_cndmask_b32_e32 v87, v214, v37, vcc
	v_cmp_lt_i32_e32 vcc, 1, v68
	v_max3_f32 v3, v86, s97, v87
	s_waitcnt lgkmcnt(2)
	v_mfma_f32_32x32x16_bf16 v[52:67], v[74:77], v[104:107], v[52:67]
	v_cndmask_b32_e32 v94, v214, v38, vcc
	v_cmp_lt_i32_e32 vcc, 2, v68
	s_nop 1
	v_cndmask_b32_e32 v95, v214, v39, vcc
	v_cmp_lt_i32_e32 vcc, 7, v68
	v_max3_f32 v3, v3, v94, v95
	s_waitcnt lgkmcnt(1)
	v_mfma_f32_32x32x16_bf16 v[52:67], v[70:73], v[108:111], v[52:67]
	v_cndmask_b32_e32 v98, v214, v40, vcc
	v_cmp_lt_i32_e32 vcc, 8, v68
	s_nop 1
	v_cndmask_b32_e32 v99, v214, v41, vcc
	v_cmp_lt_i32_e32 vcc, 9, v68
	v_max3_f32 v3, v3, v98, v99
	s_waitcnt lgkmcnt(0)
	v_mfma_f32_32x32x16_bf16 v[52:67], v[78:81], v[112:115], v[52:67]
	v_cndmask_b32_e32 v96, v214, v42, vcc
	v_cmp_lt_i32_e32 vcc, 10, v68
	s_nop 1
	v_cndmask_b32_e32 v97, v214, v43, vcc
	v_cmp_lt_i32_e32 vcc, 15, v68
	v_max3_f32 v3, v3, v96, v97
	s_nop 0
	v_cndmask_b32_e32 v170, v214, v44, vcc
	v_cmp_lt_i32_e32 vcc, 16, v68
	s_nop 1
	v_cndmask_b32_e32 v171, v214, v45, vcc
	v_cmp_lt_i32_e32 vcc, 17, v68
	v_max3_f32 v3, v3, v170, v171
	s_nop 0
	v_cndmask_b32_e32 v90, v214, v46, vcc
	v_cmp_lt_i32_e32 vcc, 18, v68
	s_nop 1
	v_cndmask_b32_e32 v91, v214, v47, vcc
	v_cmp_lt_i32_e32 vcc, 23, v68
	v_max3_f32 v3, v3, v90, v91
	s_nop 0
	v_cndmask_b32_e32 v92, v214, v48, vcc
	v_cmp_lt_i32_e32 vcc, 24, v68
	s_nop 1
	v_cndmask_b32_e32 v93, v214, v49, vcc
	v_cmp_lt_i32_e32 vcc, 25, v68
	v_max3_f32 v3, v3, v92, v93
	s_nop 0
	v_cndmask_b32_e32 v88, v214, v50, vcc
	v_cmp_lt_i32_e32 vcc, 26, v68
	s_nop 1
	v_cndmask_b32_e32 v89, v214, v51, vcc
	v_cmp_lt_i32_e32 vcc, 31, v68
	v_max3_f32 v3, v3, v88, v89
	s_nop 0
	v_cndmask_b32_e32 v84, v214, v52, vcc
	v_cmp_lt_i32_e32 vcc, 32, v68
	s_nop 1
	v_cndmask_b32_e32 v85, v214, v53, vcc
	v_cmp_lt_i32_e32 vcc, 33, v68
	v_max3_f32 v3, v3, v84, v85
	s_nop 0
	v_cndmask_b32_e32 v82, v214, v54, vcc
	v_cmp_lt_i32_e32 vcc, 34, v68
	s_nop 1
	v_cndmask_b32_e32 v83, v214, v55, vcc
	v_cmp_lt_i32_e32 vcc, 39, v68
	v_max3_f32 v3, v3, v82, v83
	s_nop 0
	v_cndmask_b32_e32 v80, v214, v56, vcc
	v_cmp_lt_i32_e32 vcc, 40, v68
	s_nop 1
	v_cndmask_b32_e32 v81, v214, v57, vcc
	v_cmp_lt_i32_e32 vcc, 41, v68
	v_max3_f32 v3, v3, v80, v81
	s_nop 0
	v_cndmask_b32_e32 v78, v214, v58, vcc
	v_cmp_lt_i32_e32 vcc, 42, v68
	s_nop 1
	v_cndmask_b32_e32 v79, v214, v59, vcc
	v_cmp_lt_i32_e32 vcc, 47, v68
	v_max3_f32 v3, v3, v78, v79
	s_nop 0
	v_cndmask_b32_e32 v76, v214, v60, vcc
	v_cmp_lt_i32_e32 vcc, 48, v68
	s_nop 1
	v_cndmask_b32_e32 v77, v214, v61, vcc
	v_cmp_lt_i32_e32 vcc, 49, v68
	v_max3_f32 v3, v3, v76, v77
	s_nop 0
	v_cndmask_b32_e32 v74, v214, v62, vcc
	v_cmp_lt_i32_e32 vcc, 50, v68
	s_nop 1
	v_cndmask_b32_e32 v75, v214, v63, vcc
	v_cmp_lt_i32_e32 vcc, 55, v68
	v_max3_f32 v3, v3, v74, v75
	s_nop 0
	v_cndmask_b32_e32 v70, v214, v64, vcc
	v_cmp_lt_i32_e32 vcc, 56, v68
	s_nop 1
	v_cndmask_b32_e32 v71, v214, v65, vcc
	v_cmp_lt_i32_e32 vcc, 57, v68
	v_max3_f32 v3, v3, v70, v71
	s_nop 0
	v_cndmask_b32_e32 v72, v214, v66, vcc
	v_cmp_lt_i32_e32 vcc, 58, v68
	s_nop 1
	v_cndmask_b32_e32 v73, v214, v67, vcc
	v_max3_f32 v3, v3, v72, v73
	ds_bpermute_b32 v36, v179, v3
	s_nop 3
	s_waitcnt lgkmcnt(0)
	v_max_f32_e32 v36, v36, v36
	v_max_f32_e32 v3, v3, v36
	v_max3_f32 v132, v218, v3, s46
	v_sub_f32_e32 v3, v218, v132
	v_exp_f32_e32 v68, v3
	s_nop 2
	v_cmp_eq_f32_e32 vcc, 1.0, v68
	s_cmp_eq_u64 vcc, exec
	s_nop 8
	s_cbranch_scc1 .LBB0_1449
	v_mul_f32_e32 v34, v34, v68
	v_mul_f32_e32 v35, v35, v68
	v_mul_f32_e32 v32, v32, v68
	v_mul_f32_e32 v33, v33, v68
	v_mul_f32_e32 v30, v30, v68
	v_mul_f32_e32 v31, v31, v68
	v_mul_f32_e32 v28, v28, v68
	v_mul_f32_e32 v29, v29, v68
	v_mul_f32_e32 v26, v26, v68
	v_mul_f32_e32 v27, v27, v68
	v_mul_f32_e32 v24, v24, v68
	v_mul_f32_e32 v25, v25, v68
	v_mul_f32_e32 v22, v22, v68
	v_mul_f32_e32 v23, v23, v68
	v_mul_f32_e32 v20, v20, v68
	v_mul_f32_e32 v21, v21, v68
	v_mul_f32_e32 v18, v18, v68
	v_mul_f32_e32 v19, v19, v68
	v_mul_f32_e32 v16, v16, v68
	v_mul_f32_e32 v17, v17, v68
	v_mul_f32_e32 v14, v14, v68
	v_mul_f32_e32 v15, v15, v68
	v_mul_f32_e32 v12, v12, v68
	v_mul_f32_e32 v13, v13, v68
	v_mul_f32_e32 v10, v10, v68
	v_mul_f32_e32 v11, v11, v68
	v_mul_f32_e32 v8, v8, v68
	v_mul_f32_e32 v9, v9, v68
	v_mul_f32_e32 v6, v6, v68
	v_mul_f32_e32 v7, v7, v68
	v_mul_f32_e32 v4, v4, v68
	v_mul_f32_e32 v5, v5, v68
.LBB0_1449:
	v_sub_f32_e32 v94, v94, v132
	v_sub_f32_e32 v95, v95, v132
	v_lshl_add_u32 v3, v136, 1, s38
	v_exp_f32_e32 v230, v94
	v_exp_f32_e32 v231, v95
	v_sub_f32_e32 v94, v98, v132
	v_sub_f32_e32 v95, v99, v132
	v_sub_f32_e32 v86, v86, v132
	v_sub_f32_e32 v87, v87, v132
	v_exp_f32_e32 v98, v94
	v_exp_f32_e32 v99, v95
	v_sub_f32_e32 v94, v96, v132
	v_sub_f32_e32 v95, v97, v132
	v_exp_f32_e32 v86, v86
	v_exp_f32_e32 v232, v94
	v_add_u32_e32 v94, v3, v190
	v_add_u32_e32 v186, 0x6800, v94
	v_exp_f32_e32 v233, v95
	ds_read2_b64 v[94:97], v186 offset0:64 offset1:66
	v_add_u32_e32 v3, v3, v191
	v_add_u32_e32 v3, 0x6800, v3
	ds_read2_b64 v[226:229], v3 offset0:64 offset1:66
	v_exp_f32_e32 v87, v87
	v_sub_f32_e32 v90, v90, v132
	v_sub_f32_e32 v91, v91, v132
	v_cvt_pk_bf16_f32 v223, v230, v231
	v_exp_f32_e32 v234, v90
	v_exp_f32_e32 v235, v91
	v_sub_f32_e32 v90, v92, v132
	v_sub_f32_e32 v91, v93, v132
	v_cvt_pk_bf16_f32 v222, v86, v87
	v_cvt_pk_bf16_f32 v224, v98, v99
	v_cvt_pk_bf16_f32 v225, v232, v233
	v_exp_f32_e32 v236, v90
	v_exp_f32_e32 v237, v91
	ds_read2_b64 v[90:93], v186 offset0:68 offset1:70
	s_waitcnt lgkmcnt(2)
	v_mfma_f32_32x32x16_bf16 v[20:35], v[94:97], v[222:225], v[20:35]
	v_add_f32_e64 v170, v170, -v132
	v_add_f32_e64 v171, v171, -v132
	v_add_f32_e64 v88, v88, -v132
	v_add_f32_e64 v89, v89, -v132
	v_exp_f32_e32 v170, v170
	v_exp_f32_e32 v171, v171
	v_cvt_pk_bf16_f32 v95, v234, v235
	v_cvt_pk_bf16_f32 v96, v236, v237
	v_cvt_pk_bf16_f32 v94, v170, v171
	s_waitcnt lgkmcnt(1)
	v_mfma_f32_32x32x16_bf16 v[4:19], v[226:229], v[222:225], v[4:19]
	v_exp_f32_e32 v222, v88
	v_exp_f32_e32 v223, v89
	s_nop 0
	v_cvt_pk_bf16_f32 v97, v222, v223
	s_waitcnt lgkmcnt(0)
	s_nop 0
	v_mfma_f32_32x32x16_bf16 v[20:35], v[90:93], v[94:97], v[20:35]
	ds_read2_b64 v[88:91], v3 offset0:68 offset1:70
	s_waitcnt lgkmcnt(0)
	v_mfma_f32_32x32x16_bf16 v[4:19], v[88:91], v[94:97], v[4:19]
	v_add_f32_e64 v80, v80, -v132
	v_add_f32_e64 v81, v81, -v132
	v_add_f32_e64 v78, v78, -v132
	v_add_f32_e64 v79, v79, -v132
	v_exp_f32_e32 v94, v80
	v_exp_f32_e32 v95, v81
	v_exp_f32_e32 v96, v78
	v_exp_f32_e32 v97, v79
	v_sub_f32_e32 v80, v76, v132
	v_sub_f32_e32 v81, v77, v132
	ds_read2_b64 v[76:79], v186 offset0:72 offset1:74
	v_sub_f32_e32 v84, v84, v132
	v_sub_f32_e32 v85, v85, v132
	v_sub_f32_e32 v82, v82, v132
	v_sub_f32_e32 v83, v83, v132
	ds_read2_b64 v[88:91], v3 offset0:72 offset1:74
	v_exp_f32_e32 v84, v84
	v_exp_f32_e32 v85, v85
	v_exp_f32_e32 v92, v82
	v_exp_f32_e32 v93, v83
	v_sub_f32_e32 v74, v74, v132
	v_sub_f32_e32 v75, v75, v132
	v_sub_f32_e32 v70, v70, v132
	v_sub_f32_e32 v71, v71, v132
	v_exp_f32_e32 v224, v80
	v_exp_f32_e32 v225, v81
	v_cvt_pk_bf16_f32 v80, v84, v85
	v_cvt_pk_bf16_f32 v81, v92, v93
	v_cvt_pk_bf16_f32 v82, v94, v95
	v_cvt_pk_bf16_f32 v83, v96, v97
	v_exp_f32_e32 v226, v74
	v_exp_f32_e32 v227, v75
	v_exp_f32_e32 v228, v70
	v_exp_f32_e32 v229, v71
	v_sub_f32_e32 v74, v72, v132
	v_sub_f32_e32 v75, v73, v132
	ds_read2_b64 v[70:73], v186 offset0:76 offset1:78
	s_waitcnt lgkmcnt(2)
	v_mfma_f32_32x32x16_bf16 v[20:35], v[76:79], v[80:83], v[20:35]
	v_cvt_pk_bf16_f32 v78, v224, v225
	v_cvt_pk_bf16_f32 v79, v226, v227
	s_mov_b64 s[24:25], 0
	s_waitcnt lgkmcnt(1)
	v_mfma_f32_32x32x16_bf16 v[4:19], v[88:91], v[80:83], v[4:19]
	v_exp_f32_e32 v82, v74
	v_exp_f32_e32 v83, v75
	v_cvt_pk_bf16_f32 v80, v228, v229
	ds_read2_b64 v[74:77], v3 offset0:76 offset1:78
	v_cvt_pk_bf16_f32 v81, v82, v83
	s_waitcnt lgkmcnt(1)
	s_nop 0
	v_mfma_f32_32x32x16_bf16 v[20:35], v[70:73], v[78:81], v[20:35]
	v_add_f32_e64 v70, v86, 0
	v_add_f32_e64 v71, v87, 0
	v_add_f32_e64 v70, v230, v70
	v_add_f32_e64 v71, v231, v71
	v_add_f32_e64 v70, v98, v70
	v_add_f32_e64 v71, v99, v71
	v_add_f32_e32 v70, v232, v70
	v_add_f32_e32 v71, v233, v71
	s_waitcnt lgkmcnt(0)
	v_mfma_f32_32x32x16_bf16 v[4:19], v[74:77], v[78:81], v[4:19]
	v_add_f32_e64 v70, v170, v70
	v_add_f32_e64 v71, v171, v71
	v_add_f32_e64 v70, v234, v70
	v_add_f32_e64 v71, v235, v71
	v_add_f32_e64 v70, v236, v70
	v_add_f32_e64 v71, v237, v71
	v_add_f32_e32 v70, v222, v70
	v_add_f32_e32 v71, v223, v71
	s_nop 0
	v_add_f32_e32 v70, v84, v70
	v_add_f32_e32 v71, v85, v71
	s_nop 0
	v_add_f32_e32 v70, v92, v70
	v_add_f32_e32 v71, v93, v71
	s_nop 0
	v_add_f32_e32 v70, v94, v70
	v_add_f32_e32 v71, v95, v71
	s_nop 0
	v_add_f32_e32 v70, v96, v70
	v_add_f32_e32 v71, v97, v71
	s_nop 0
	v_add_f32_e32 v70, v224, v70
	v_add_f32_e32 v71, v225, v71
	s_nop 0
	v_add_f32_e32 v70, v226, v70
	v_add_f32_e32 v71, v227, v71
	s_nop 0
	v_add_f32_e32 v70, v228, v70
	v_add_f32_e32 v71, v229, v71
	s_nop 0
	v_add_f32_e32 v70, v82, v70
	v_add_f32_e32 v71, v83, v71
	s_nop 0
	v_add_f32_e32 v3, v70, v71
	ds_bpermute_b32 v70, v179, v3
	s_waitcnt lgkmcnt(0)
	v_add_f32_e32 v3, v3, v70
	v_fmac_f32_e32 v3, v217, v68
.LBB0_1450:
	s_and_b64 vcc, exec, s[24:25]
	s_cbranch_vccz .LBB0_1463
	v_mov_b32_e32 v3, v157
	s_nop 0
	v_mul_f32_e64 v36, v69, -v3
	v_cndmask_b32_e64 v44, v214, v36, s[0:1]
	v_mov_b32_e32 v46, v3
	v_fma_f32 v36, 0, v3, v44
	v_add_f32_e32 v84, v2, v36
	v_add_f32_e32 v85, v3, v36
	v_fma_f32 v86, v46, s64, v36
	v_fma_f32 v87, v46, s65, v36
	ds_read_b128 v[36:39], v220 offset:17920
	v_fmamk_f32 v40, v3, 0x41000000, v44
	v_add_f32_e32 v88, v2, v40
	v_add_f32_e32 v89, v3, v40
	v_fma_f32 v90, v46, s64, v40
	v_fma_f32 v91, v46, s65, v40
	v_fmamk_f32 v40, v3, 0x41800000, v44
	v_add_f32_e32 v92, v2, v40
	v_add_f32_e32 v93, v3, v40
	v_fma_f32 v94, v46, s64, v40
	v_fma_f32 v95, v46, s65, v40
	v_fmamk_f32 v40, v3, 0x41c00000, v44
	v_add_f32_e32 v96, v2, v40
	v_add_f32_e32 v97, v3, v40
	v_fma_f32 v98, v46, s64, v40
	v_fma_f32 v99, v46, s65, v40
	ds_read_b128 v[40:43], v220 offset:17952
	v_fmamk_f32 v48, v3, 0x42000000, v44
	s_waitcnt lgkmcnt(1)
	v_mfma_f32_32x32x16_bf16 v[84:99], v[36:39], v[100:103], v[84:99]
	v_fmamk_f32 v50, v3, 0x42200000, v44
	v_fmamk_f32 v52, v3, 0x42400000, v44
	v_fmac_f32_e32 v44, 0x42600000, v3
	v_add_f32_e64 v68, v2, v48
	v_add_f32_e64 v69, v3, v48
	v_fma_f32 v70, v46, s64, v48
	v_fma_f32 v71, v46, s65, v48
	v_add_f32_e32 v72, v2, v50
	v_add_f32_e32 v73, v3, v50
	v_fma_f32 v74, v46, s64, v50
	v_fma_f32 v75, v46, s65, v50
	s_waitcnt lgkmcnt(0)
	v_mfma_f32_32x32x16_bf16 v[84:99], v[40:43], v[104:107], v[84:99]
	ds_read_b128 v[36:39], v220 offset:17984
	ds_read_b128 v[40:43], v220 offset:18016
	v_add_f32_e64 v76, v2, v52
	v_add_f32_e64 v77, v3, v52
	v_fma_f32 v78, v46, s64, v52
	v_fma_f32 v79, v46, s65, v52
	v_add_f32_e32 v80, v2, v44
	v_add_f32_e32 v81, v3, v44
	v_fma_f32 v82, v46, s64, v44
	v_fma_f32 v83, v46, s65, v44
	s_nop 1
	s_waitcnt lgkmcnt(1)
	v_mfma_f32_32x32x16_bf16 v[84:99], v[36:39], v[108:111], v[84:99]
	ds_read_b128 v[36:39], v219 offset:17920
	s_nop 5
	s_waitcnt lgkmcnt(1)
	v_mfma_f32_32x32x16_bf16 v[84:99], v[40:43], v[112:115], v[84:99]
	ds_read_b128 v[40:43], v219 offset:17952
	s_waitcnt lgkmcnt(1)
	v_mfma_f32_32x32x16_bf16 v[68:83], v[36:39], v[100:103], v[68:83]
	s_nop 8
	v_max3_f32 v3, v84, s97, v85
	v_max3_f32 v3, v3, v86, v87
	v_max3_f32 v3, v3, v88, v89
	v_max3_f32 v3, v3, v90, v91
	v_max3_f32 v3, v3, v92, v93
	v_max3_f32 v3, v3, v94, v95
	v_max3_f32 v3, v3, v96, v97
	s_waitcnt lgkmcnt(0)
	v_mfma_f32_32x32x16_bf16 v[68:83], v[40:43], v[104:107], v[68:83]
	ds_read_b128 v[36:39], v219 offset:17984
	ds_read_b128 v[40:43], v219 offset:18016
	v_max3_f32 v3, v3, v98, v99
	s_waitcnt lgkmcnt(1)
	v_mfma_f32_32x32x16_bf16 v[68:83], v[36:39], v[108:111], v[68:83]
	s_waitcnt lgkmcnt(0)
	v_mfma_f32_32x32x16_bf16 v[68:83], v[40:43], v[112:115], v[68:83]
	s_nop 11
	v_max3_f32 v3, v3, v68, v69
	v_max3_f32 v3, v3, v70, v71
	v_max3_f32 v3, v3, v72, v73
	v_max3_f32 v3, v3, v74, v75
	v_max3_f32 v3, v3, v76, v77
	v_max3_f32 v3, v3, v78, v79
	v_max3_f32 v3, v3, v80, v81
	v_max3_f32 v3, v3, v82, v83
	ds_bpermute_b32 v36, v179, v3
	s_waitcnt lgkmcnt(0)
	v_max_f32_e32 v36, v36, v36
	v_max_f32_e32 v3, v3, v36
	v_max3_f32 v132, v218, v3, s46
	v_sub_f32_e32 v3, v218, v132
	v_exp_f32_e32 v170, v3
	s_nop 2
	v_cmp_eq_f32_e32 vcc, 1.0, v170
	s_cmp_eq_u64 vcc, exec
	s_nop 4
	s_cbranch_scc1 .LBB0_1453
	v_mul_f32_e32 v34, v34, v170
	v_mul_f32_e32 v35, v35, v170
	v_mul_f32_e32 v32, v32, v170
	v_mul_f32_e32 v33, v33, v170
	v_mul_f32_e32 v30, v30, v170
	v_mul_f32_e32 v31, v31, v170
	v_mul_f32_e32 v28, v28, v170
	v_mul_f32_e32 v29, v29, v170
	v_mul_f32_e32 v26, v26, v170
	v_mul_f32_e32 v27, v27, v170
	v_mul_f32_e32 v24, v24, v170
	v_mul_f32_e32 v25, v25, v170
	v_mul_f32_e32 v22, v22, v170
	v_mul_f32_e32 v23, v23, v170
	v_mul_f32_e32 v20, v20, v170
	v_mul_f32_e32 v21, v21, v170
	v_mul_f32_e32 v18, v18, v170
	v_mul_f32_e32 v19, v19, v170
	v_mul_f32_e32 v16, v16, v170
	v_mul_f32_e32 v17, v17, v170
	v_mul_f32_e32 v14, v14, v170
	v_mul_f32_e32 v15, v15, v170
	v_mul_f32_e32 v12, v12, v170
	v_mul_f32_e32 v13, v13, v170
	v_mul_f32_e32 v10, v10, v170
	v_mul_f32_e32 v11, v11, v170
	v_mul_f32_e32 v8, v8, v170
	v_mul_f32_e32 v9, v9, v170
	v_mul_f32_e32 v6, v6, v170
	v_mul_f32_e32 v7, v7, v170
	v_mul_f32_e32 v4, v4, v170
	v_mul_f32_e32 v5, v5, v170
.LBB0_1453:
	v_add_u32_e32 v3, v165, v196
	v_sub_f32_e32 v84, v84, v132
	v_sub_f32_e32 v85, v85, v132
	v_sub_f32_e32 v86, v86, v132
	v_sub_f32_e32 v87, v87, v132
	v_sub_f32_e32 v88, v88, v132
	v_sub_f32_e32 v89, v89, v132
	v_sub_f32_e32 v90, v90, v132
	v_sub_f32_e32 v91, v91, v132
	v_add_u32_e32 v171, v3, v190
	v_exp_f32_e32 v84, v84
	v_exp_f32_e32 v85, v85
	v_exp_f32_e32 v86, v86
	v_exp_f32_e32 v87, v87
	v_exp_f32_e32 v88, v88
	v_exp_f32_e32 v89, v89
	v_exp_f32_e32 v90, v90
	v_exp_f32_e32 v91, v91
	v_add_u32_e32 v171, 0x6800, v171
	ds_read2_b64 v[226:229], v171 offset0:64 offset1:66
	ds_read2_b64 v[230:233], v171 offset0:68 offset1:70
	v_add_u32_e32 v3, v3, v191
	v_cvt_pk_bf16_f32 v222, v84, v85
	v_cvt_pk_bf16_f32 v223, v86, v87
	v_cvt_pk_bf16_f32 v224, v88, v89
	v_cvt_pk_bf16_f32 v225, v90, v91
	v_add_u32_e32 v3, 0x6800, v3
	v_sub_f32_e32 v92, v92, v132
	v_sub_f32_e32 v93, v93, v132
	s_waitcnt lgkmcnt(1)
	v_mfma_f32_32x32x16_bf16 v[20:35], v[226:229], v[222:225], v[20:35]
	ds_read2_b64 v[226:229], v3 offset0:64 offset1:66
	ds_read2_b64 v[234:237], v3 offset0:68 offset1:70
	v_add_f32_e64 v94, v94, -v132
	v_add_f32_e64 v95, v95, -v132
	v_add_f32_e64 v96, v96, -v132
	v_add_f32_e64 v97, v97, -v132
	v_sub_f32_e32 v98, v98, v132
	v_sub_f32_e32 v99, v99, v132
	v_exp_f32_e32 v92, v92
	v_exp_f32_e32 v93, v93
	v_exp_f32_e32 v94, v94
	s_waitcnt lgkmcnt(1)
	v_mfma_f32_32x32x16_bf16 v[4:19], v[226:229], v[222:225], v[4:19]
	v_exp_f32_e32 v95, v95
	v_exp_f32_e32 v96, v96
	v_exp_f32_e32 v97, v97
	v_exp_f32_e32 v98, v98
	v_exp_f32_e32 v99, v99
	v_cvt_pk_bf16_f32 v222, v92, v93
	v_cvt_pk_bf16_f32 v223, v94, v95
	v_cvt_pk_bf16_f32 v224, v96, v97
	v_cvt_pk_bf16_f32 v225, v98, v99
	s_nop 1
	v_mfma_f32_32x32x16_bf16 v[20:35], v[230:233], v[222:225], v[20:35]
	s_waitcnt lgkmcnt(0)
	v_mfma_f32_32x32x16_bf16 v[4:19], v[234:237], v[222:225], v[4:19]
	v_add_f32_e64 v74, v74, -v132
	v_add_f32_e64 v75, v75, -v132
	v_add_f32_e64 v68, v68, -v132
	v_add_f32_e64 v69, v69, -v132
	v_add_f32_e64 v70, v70, -v132
	v_add_f32_e64 v71, v71, -v132
	v_sub_f32_e32 v72, v72, v132
	v_sub_f32_e32 v73, v73, v132
	v_exp_f32_e32 v230, v74
	v_exp_f32_e32 v231, v75
	v_sub_f32_e32 v74, v76, v132
	v_sub_f32_e32 v75, v77, v132
	v_exp_f32_e32 v68, v68
	v_exp_f32_e32 v69, v69
	v_exp_f32_e32 v70, v70
	v_exp_f32_e32 v71, v71
	v_exp_f32_e32 v72, v72
	v_exp_f32_e32 v73, v73
	v_exp_f32_e32 v232, v74
	v_exp_f32_e32 v233, v75
	v_sub_f32_e32 v74, v78, v132
	v_sub_f32_e32 v75, v79, v132
	v_cvt_pk_bf16_f32 v76, v72, v73
	v_exp_f32_e32 v234, v74
	v_exp_f32_e32 v235, v75
	v_sub_f32_e32 v74, v80, v132
	v_sub_f32_e32 v75, v81, v132
	ds_read2_b64 v[78:81], v171 offset0:72 offset1:74
	ds_read2_b64 v[222:225], v171 offset0:76 offset1:78
	v_exp_f32_e32 v236, v74
	v_exp_f32_e32 v237, v75
	v_sub_f32_e32 v74, v82, v132
	v_sub_f32_e32 v75, v83, v132
	v_cvt_pk_bf16_f32 v77, v230, v231
	v_exp_f32_e32 v82, v74
	v_exp_f32_e32 v83, v75
	v_cvt_pk_bf16_f32 v74, v68, v69
	v_cvt_pk_bf16_f32 v75, v70, v71
	s_mov_b64 s[24:25], 0
	s_waitcnt lgkmcnt(1)
	v_mfma_f32_32x32x16_bf16 v[20:35], v[78:81], v[74:77], v[20:35]
	ds_read2_b64 v[78:81], v3 offset0:72 offset1:74
	ds_read2_b64 v[226:229], v3 offset0:76 offset1:78
	s_waitcnt lgkmcnt(1)
	v_mfma_f32_32x32x16_bf16 v[4:19], v[78:81], v[74:77], v[4:19]
	v_cvt_pk_bf16_f32 v74, v232, v233
	v_cvt_pk_bf16_f32 v75, v234, v235
	v_cvt_pk_bf16_f32 v76, v236, v237
	v_cvt_pk_bf16_f32 v77, v82, v83
	s_nop 1
	v_mfma_f32_32x32x16_bf16 v[20:35], v[222:225], v[74:77], v[20:35]
	s_waitcnt lgkmcnt(0)
	v_mfma_f32_32x32x16_bf16 v[4:19], v[226:229], v[74:77], v[4:19]
	v_add_f32_e64 v74, v84, 0
	v_add_f32_e64 v75, v85, 0
	v_add_f32_e64 v74, v86, v74
	v_add_f32_e64 v75, v87, v75
	v_add_f32_e64 v74, v88, v74
	v_add_f32_e64 v75, v89, v75
	v_add_f32_e32 v74, v90, v74
	v_add_f32_e32 v75, v91, v75
	s_nop 0
	v_add_f32_e32 v74, v92, v74
	v_add_f32_e32 v75, v93, v75
	s_nop 0
	v_add_f32_e32 v74, v94, v74
	v_add_f32_e32 v75, v95, v75
	s_nop 0
	v_add_f32_e32 v74, v96, v74
	v_add_f32_e32 v75, v97, v75
	s_nop 0
	v_add_f32_e32 v74, v98, v74
	v_add_f32_e32 v75, v99, v75
	s_nop 0
	v_add_f32_e32 v68, v68, v74
	v_add_f32_e32 v69, v69, v75
	s_nop 0
	v_add_f32_e32 v68, v70, v68
	v_add_f32_e32 v69, v71, v69
	s_nop 0
	v_add_f32_e32 v68, v72, v68
	v_add_f32_e32 v69, v73, v69
	s_nop 0
	v_add_f32_e32 v68, v230, v68
	v_add_f32_e32 v69, v231, v69
	s_nop 0
	v_add_f32_e32 v68, v232, v68
	v_add_f32_e32 v69, v233, v69
	s_nop 0
	v_add_f32_e32 v68, v234, v68
	v_add_f32_e32 v69, v235, v69
	s_nop 0
	v_add_f32_e32 v68, v236, v68
	v_add_f32_e32 v69, v237, v69
	s_nop 0
	v_add_f32_e32 v68, v82, v68
	v_add_f32_e32 v69, v83, v69
	s_nop 0
	v_add_f32_e32 v3, v68, v69
	ds_bpermute_b32 v68, v179, v3
	s_waitcnt lgkmcnt(0)
	v_add_f32_e32 v3, v3, v68
	v_fmac_f32_e32 v3, v217, v170

.LBB0_1455:
	v_sub_u32_e32 v68, v161, v221
	s_cmp_gt_i32 s39, s76
	v_cvt_f32_i32_e32 v69, v68
	s_cselect_b64 s[0:1], -1, 0
	s_and_b64 s[0:1], s[2:3], s[0:1]
	s_andn2_b64 vcc, exec, s[0:1]
	s_mov_b64 s[0:1], -1
	s_cbranch_vccz .LBB0_1459
	v_mov_b32_e32 v3, v157
	ds_read_b128 v[52:55], v220 offset:17920
	ds_read_b128 v[56:59], v220 offset:17952
	v_mul_f32_e64 v66, v69, -v3
	v_mov_b32_e32 v78, v3
	v_fma_f32 v38, 0, v3, v66
	v_fmamk_f32 v42, v3, 0x41000000, v66
	v_fmamk_f32 v46, v3, 0x41800000, v66
	v_fmamk_f32 v50, v3, 0x41c00000, v66
	v_add_f32_e32 v36, v2, v38
	v_add_f32_e32 v37, v3, v38
	v_fma_f32 v39, v78, s65, v38
	v_fma_f32 v38, v78, s64, v38
	v_add_f32_e32 v40, v2, v42
	v_add_f32_e32 v41, v3, v42
	v_fma_f32 v43, v78, s65, v42
	v_fma_f32 v42, v78, s64, v42
	v_add_f32_e32 v44, v2, v46
	v_add_f32_e32 v45, v3, v46
	v_fma_f32 v47, v78, s65, v46
	v_fma_f32 v46, v78, s64, v46
	v_add_f32_e32 v48, v2, v50
	v_add_f32_e32 v49, v3, v50
	v_fma_f32 v51, v78, s65, v50
	v_fma_f32 v50, v78, s64, v50
	v_fmamk_f32 v60, v3, 0x42200000, v66
	v_fmamk_f32 v62, v3, 0x42400000, v66
	s_waitcnt lgkmcnt(1)
	v_mfma_f32_32x32x16_bf16 v[36:51], v[52:55], v[100:103], v[36:51]
	v_cmp_gt_u32_e32 vcc, s47, v68
	s_waitcnt lgkmcnt(0)
	v_mfma_f32_32x32x16_bf16 v[36:51], v[56:59], v[104:107], v[36:51]
	ds_read_b128 v[52:55], v220 offset:17984
	ds_read_b128 v[56:59], v220 offset:18016
	ds_read_b128 v[70:73], v219 offset:17920
	ds_read_b128 v[74:77], v219 offset:17952
	s_waitcnt lgkmcnt(3)
	v_mfma_f32_32x32x16_bf16 v[36:51], v[52:55], v[108:111], v[36:51]
	v_fmamk_f32 v54, v3, 0x42000000, v66
	v_fmac_f32_e32 v66, 0x42600000, v3
	v_add_f32_e64 v52, v2, v54
	v_add_f32_e64 v53, v3, v54
	v_fma_f32 v55, v78, s65, v54
	v_fma_f32 v54, v78, s64, v54
	v_add_f32_e32 v64, v2, v66
	v_add_f32_e32 v65, v3, v66
	v_fma_f32 v67, v78, s65, v66
	v_fma_f32 v66, v78, s64, v66
	s_waitcnt lgkmcnt(2)
	v_mfma_f32_32x32x16_bf16 v[36:51], v[56:59], v[112:115], v[36:51]
	v_add_f32_e64 v56, v2, v60
	v_add_f32_e64 v57, v3, v60
	v_fma_f32 v58, v78, s64, v60
	v_fma_f32 v59, v78, s65, v60
	v_add_f32_e64 v60, v2, v62
	v_add_f32_e64 v61, v3, v62
	v_fma_f32 v63, v78, s65, v62
	v_fma_f32 v62, v78, s64, v62
	v_add_u32_e32 v3, -1, v68
	s_nop 3
	v_cndmask_b32_e32 v88, v214, v36, vcc
	s_waitcnt lgkmcnt(1)
	v_mfma_f32_32x32x16_bf16 v[52:67], v[70:73], v[100:103], v[52:67]
	ds_read_b128 v[70:73], v219 offset:17984
	ds_read_b128 v[78:81], v219 offset:18016
	v_cmp_gt_u32_e32 vcc, s47, v3
	v_add_u32_e32 v36, -2, v68
	s_nop 0
	v_cndmask_b32_e32 v89, v214, v37, vcc
	v_cmp_gt_u32_e32 vcc, s47, v36
	v_add_u32_e32 v36, -3, v68
	s_waitcnt lgkmcnt(2)
	v_mfma_f32_32x32x16_bf16 v[52:67], v[74:77], v[104:107], v[52:67]
	v_cndmask_b32_e32 v94, v214, v38, vcc
	v_cmp_gt_u32_e32 vcc, s47, v36
	v_add_u32_e32 v36, -8, v68
	v_max3_f32 v3, v88, s97, v89
	v_cndmask_b32_e32 v95, v214, v39, vcc
	v_cmp_gt_u32_e32 vcc, s47, v36
	v_add_u32_e32 v36, -9, v68
	s_waitcnt lgkmcnt(1)
	v_mfma_f32_32x32x16_bf16 v[52:67], v[70:73], v[108:111], v[52:67]
	v_cndmask_b32_e32 v96, v214, v40, vcc
	v_cmp_gt_u32_e32 vcc, s47, v36
	v_add_u32_e32 v36, -10, v68
	v_max3_f32 v3, v3, v94, v95
	v_cndmask_b32_e32 v97, v214, v41, vcc
	v_cmp_gt_u32_e32 vcc, s47, v36
	v_add_u32_e32 v36, -11, v68
	s_waitcnt lgkmcnt(0)
	v_mfma_f32_32x32x16_bf16 v[52:67], v[78:81], v[112:115], v[52:67]
	v_cndmask_b32_e32 v98, v214, v42, vcc
	v_cmp_gt_u32_e32 vcc, s47, v36
	v_add_u32_e32 v36, -16, v68
	v_max3_f32 v3, v3, v96, v97
	v_cndmask_b32_e32 v99, v214, v43, vcc
	v_cmp_gt_u32_e32 vcc, s47, v36
	v_subrev_u32_e32 v36, 17, v68
	v_max3_f32 v3, v3, v98, v99
	v_cndmask_b32_e32 v170, v214, v44, vcc
	v_cmp_gt_u32_e32 vcc, s47, v36
	v_subrev_u32_e32 v36, 18, v68
	s_nop 0
	v_cndmask_b32_e32 v171, v214, v45, vcc
	v_cmp_gt_u32_e32 vcc, s47, v36
	v_subrev_u32_e32 v36, 19, v68
	v_max3_f32 v3, v3, v170, v171
	v_cndmask_b32_e32 v90, v214, v46, vcc
	v_cmp_gt_u32_e32 vcc, s47, v36
	v_subrev_u32_e32 v36, 24, v68
	s_nop 0
	v_cndmask_b32_e32 v91, v214, v47, vcc
	v_cmp_gt_u32_e32 vcc, s47, v36
	v_subrev_u32_e32 v36, 25, v68
	v_max3_f32 v3, v3, v90, v91
	v_cndmask_b32_e32 v92, v214, v48, vcc
	v_cmp_gt_u32_e32 vcc, s47, v36
	v_subrev_u32_e32 v36, 26, v68
	s_nop 0
	v_cndmask_b32_e32 v93, v214, v49, vcc
	v_cmp_gt_u32_e32 vcc, s47, v36
	v_subrev_u32_e32 v36, 27, v68
	v_max3_f32 v3, v3, v92, v93
	v_cndmask_b32_e32 v86, v214, v50, vcc
	v_cmp_gt_u32_e32 vcc, s47, v36
	v_subrev_u32_e32 v36, 32, v68
	s_nop 0
	v_cndmask_b32_e32 v87, v214, v51, vcc
	v_cmp_gt_u32_e32 vcc, s47, v36
	v_subrev_u32_e32 v36, 33, v68
	v_max3_f32 v3, v3, v86, v87
	v_cndmask_b32_e32 v76, v214, v52, vcc
	v_cmp_gt_u32_e32 vcc, s47, v36
	v_subrev_u32_e32 v36, 34, v68
	s_nop 0
	v_cndmask_b32_e32 v77, v214, v53, vcc
	v_cmp_gt_u32_e32 vcc, s47, v36
	v_subrev_u32_e32 v36, 35, v68
	v_max3_f32 v3, v3, v76, v77
	v_cndmask_b32_e32 v78, v214, v54, vcc
	v_cmp_gt_u32_e32 vcc, s47, v36
	v_subrev_u32_e32 v36, 40, v68
	s_nop 0
	v_cndmask_b32_e32 v79, v214, v55, vcc
	v_cmp_gt_u32_e32 vcc, s47, v36
	v_subrev_u32_e32 v36, 41, v68
	v_max3_f32 v3, v3, v78, v79
	v_cndmask_b32_e32 v80, v214, v56, vcc
	v_cmp_gt_u32_e32 vcc, s47, v36
	v_subrev_u32_e32 v36, 42, v68
	s_nop 0
	v_cndmask_b32_e32 v81, v214, v57, vcc
	v_cmp_gt_u32_e32 vcc, s47, v36
	v_subrev_u32_e32 v36, 43, v68
	v_max3_f32 v3, v3, v80, v81
	v_cndmask_b32_e32 v82, v214, v58, vcc
	v_cmp_gt_u32_e32 vcc, s47, v36
	v_subrev_u32_e32 v36, 48, v68
	s_nop 0
	v_cndmask_b32_e32 v83, v214, v59, vcc
	v_cmp_gt_u32_e32 vcc, s47, v36
	v_subrev_u32_e32 v36, 49, v68
	v_max3_f32 v3, v3, v82, v83
	v_cndmask_b32_e32 v84, v214, v60, vcc
	v_cmp_gt_u32_e32 vcc, s47, v36
	v_subrev_u32_e32 v36, 50, v68
	s_nop 0
	v_cndmask_b32_e32 v85, v214, v61, vcc
	v_cmp_gt_u32_e32 vcc, s47, v36
	v_subrev_u32_e32 v36, 51, v68
	v_max3_f32 v3, v3, v84, v85
	v_cndmask_b32_e32 v74, v214, v62, vcc
	v_cmp_gt_u32_e32 vcc, s47, v36
	v_subrev_u32_e32 v36, 56, v68
	s_nop 0
	v_cndmask_b32_e32 v75, v214, v63, vcc
	v_cmp_gt_u32_e32 vcc, s47, v36
	v_subrev_u32_e32 v36, 57, v68
	v_max3_f32 v3, v3, v74, v75
	v_cndmask_b32_e32 v70, v214, v64, vcc
	v_cmp_gt_u32_e32 vcc, s47, v36
	v_subrev_u32_e32 v36, 58, v68
	s_nop 0
	v_cndmask_b32_e32 v71, v214, v65, vcc
	v_cmp_gt_u32_e32 vcc, s47, v36
	v_subrev_u32_e32 v36, 59, v68
	v_max3_f32 v3, v3, v70, v71
	v_cndmask_b32_e32 v72, v214, v66, vcc
	v_cmp_gt_u32_e32 vcc, s47, v36
	s_nop 1
	v_cndmask_b32_e32 v73, v214, v67, vcc
	v_max3_f32 v3, v3, v72, v73
	ds_bpermute_b32 v36, v179, v3
	s_nop 3
	s_waitcnt lgkmcnt(0)
	v_max_f32_e32 v36, v36, v36
	v_max_f32_e32 v3, v3, v36
	v_max3_f32 v132, v218, v3, s46
	v_sub_f32_e32 v3, v218, v132
	v_exp_f32_e32 v68, v3
	s_nop 2
	v_cmp_eq_f32_e32 vcc, 1.0, v68
	s_cmp_eq_u64 vcc, exec
	s_nop 8
	s_cbranch_scc1 .LBB0_1458
	v_mul_f32_e32 v34, v34, v68
	v_mul_f32_e32 v35, v35, v68
	v_mul_f32_e32 v32, v32, v68
	v_mul_f32_e32 v33, v33, v68
	v_mul_f32_e32 v30, v30, v68
	v_mul_f32_e32 v31, v31, v68
	v_mul_f32_e32 v28, v28, v68
	v_mul_f32_e32 v29, v29, v68
	v_mul_f32_e32 v26, v26, v68
	v_mul_f32_e32 v27, v27, v68
	v_mul_f32_e32 v24, v24, v68
	v_mul_f32_e32 v25, v25, v68
	v_mul_f32_e32 v22, v22, v68
	v_mul_f32_e32 v23, v23, v68
	v_mul_f32_e32 v20, v20, v68
	v_mul_f32_e32 v21, v21, v68
	v_mul_f32_e32 v18, v18, v68
	v_mul_f32_e32 v19, v19, v68
	v_mul_f32_e32 v16, v16, v68
	v_mul_f32_e32 v17, v17, v68
	v_mul_f32_e32 v14, v14, v68
	v_mul_f32_e32 v15, v15, v68
	v_mul_f32_e32 v12, v12, v68
	v_mul_f32_e32 v13, v13, v68
	v_mul_f32_e32 v10, v10, v68
	v_mul_f32_e32 v11, v11, v68
	v_mul_f32_e32 v8, v8, v68
	v_mul_f32_e32 v9, v9, v68
	v_mul_f32_e32 v6, v6, v68
	v_mul_f32_e32 v7, v7, v68
	v_mul_f32_e32 v4, v4, v68
	v_mul_f32_e32 v5, v5, v68
.LBB0_1458:
	v_sub_f32_e32 v94, v94, v132
	v_sub_f32_e32 v95, v95, v132
	v_lshl_add_u32 v3, v136, 1, s38
	v_exp_f32_e32 v230, v94
	v_exp_f32_e32 v231, v95
	v_sub_f32_e32 v94, v96, v132
	v_sub_f32_e32 v95, v97, v132
	v_sub_f32_e32 v88, v88, v132
	v_sub_f32_e32 v89, v89, v132
	v_exp_f32_e32 v232, v94
	v_exp_f32_e32 v233, v95
	v_sub_f32_e32 v94, v98, v132
	v_sub_f32_e32 v95, v99, v132
	v_exp_f32_e32 v88, v88
	v_exp_f32_e32 v98, v94
	v_add_u32_e32 v94, v3, v190
	v_add_u32_e32 v186, 0x6800, v94
	v_exp_f32_e32 v99, v95
	ds_read2_b64 v[94:97], v186 offset0:64 offset1:66
	v_add_u32_e32 v3, v3, v191
	v_add_u32_e32 v3, 0x6800, v3
	ds_read2_b64 v[226:229], v3 offset0:64 offset1:66
	v_exp_f32_e32 v89, v89
	v_sub_f32_e32 v90, v90, v132
	v_sub_f32_e32 v91, v91, v132
	v_cvt_pk_bf16_f32 v223, v230, v231
	v_exp_f32_e32 v234, v90
	v_exp_f32_e32 v235, v91
	v_sub_f32_e32 v90, v92, v132
	v_sub_f32_e32 v91, v93, v132
	v_cvt_pk_bf16_f32 v222, v88, v89
	v_cvt_pk_bf16_f32 v224, v232, v233
	v_cvt_pk_bf16_f32 v225, v98, v99
	v_exp_f32_e32 v236, v90
	v_exp_f32_e32 v237, v91
	ds_read2_b64 v[90:93], v186 offset0:68 offset1:70
	s_waitcnt lgkmcnt(2)
	v_mfma_f32_32x32x16_bf16 v[20:35], v[94:97], v[222:225], v[20:35]
	v_add_f32_e64 v170, v170, -v132
	v_add_f32_e64 v171, v171, -v132
	v_add_f32_e64 v86, v86, -v132
	v_add_f32_e64 v87, v87, -v132
	v_exp_f32_e32 v170, v170
	v_exp_f32_e32 v171, v171
	v_cvt_pk_bf16_f32 v95, v234, v235
	v_cvt_pk_bf16_f32 v96, v236, v237
	v_cvt_pk_bf16_f32 v94, v170, v171
	s_waitcnt lgkmcnt(1)
	v_mfma_f32_32x32x16_bf16 v[4:19], v[226:229], v[222:225], v[4:19]
	v_exp_f32_e32 v222, v86
	v_exp_f32_e32 v223, v87
	s_nop 0
	v_cvt_pk_bf16_f32 v97, v222, v223
	s_waitcnt lgkmcnt(0)
	s_nop 0
	v_mfma_f32_32x32x16_bf16 v[20:35], v[90:93], v[94:97], v[20:35]
	ds_read2_b64 v[90:93], v3 offset0:68 offset1:70
	s_waitcnt lgkmcnt(0)
	v_mfma_f32_32x32x16_bf16 v[4:19], v[90:93], v[94:97], v[4:19]
	v_add_f32_e64 v76, v76, -v132
	v_add_f32_e64 v77, v77, -v132
	v_add_f32_e64 v74, v74, -v132
	v_add_f32_e64 v75, v75, -v132
	v_exp_f32_e32 v90, v76
	v_exp_f32_e32 v91, v77
	v_sub_f32_e32 v76, v78, v132
	v_sub_f32_e32 v77, v79, v132
	v_sub_f32_e32 v70, v70, v132
	v_sub_f32_e32 v71, v71, v132
	v_exp_f32_e32 v92, v76
	v_exp_f32_e32 v93, v77
	v_sub_f32_e32 v76, v80, v132
	v_sub_f32_e32 v77, v81, v132
	v_sub_f32_e32 v80, v84, v132
	v_sub_f32_e32 v81, v85, v132
	v_exp_f32_e32 v94, v76
	v_exp_f32_e32 v95, v77
	v_sub_f32_e32 v76, v82, v132
	v_sub_f32_e32 v77, v83, v132
	ds_read2_b64 v[84:87], v3 offset0:72 offset1:74
	v_exp_f32_e32 v96, v76
	v_exp_f32_e32 v97, v77
	ds_read2_b64 v[76:79], v186 offset0:72 offset1:74
	v_exp_f32_e32 v224, v80
	v_exp_f32_e32 v225, v81
	v_cvt_pk_bf16_f32 v80, v90, v91
	v_cvt_pk_bf16_f32 v81, v92, v93
	v_cvt_pk_bf16_f32 v82, v94, v95
	v_cvt_pk_bf16_f32 v83, v96, v97
	v_exp_f32_e32 v226, v74
	v_exp_f32_e32 v227, v75
	v_exp_f32_e32 v228, v70
	v_exp_f32_e32 v229, v71
	v_sub_f32_e32 v74, v72, v132
	v_sub_f32_e32 v75, v73, v132
	ds_read2_b64 v[70:73], v186 offset0:76 offset1:78
	s_waitcnt lgkmcnt(1)
	v_mfma_f32_32x32x16_bf16 v[20:35], v[76:79], v[80:83], v[20:35]
	v_cvt_pk_bf16_f32 v78, v224, v225
	v_cvt_pk_bf16_f32 v79, v226, v227
	s_mov_b64 s[0:1], 0
	v_mfma_f32_32x32x16_bf16 v[4:19], v[84:87], v[80:83], v[4:19]
	v_exp_f32_e32 v82, v74
	v_exp_f32_e32 v83, v75
	v_cvt_pk_bf16_f32 v80, v228, v229
	ds_read2_b64 v[74:77], v3 offset0:76 offset1:78
	v_cvt_pk_bf16_f32 v81, v82, v83
	s_waitcnt lgkmcnt(1)
	s_nop 0
	v_mfma_f32_32x32x16_bf16 v[20:35], v[70:73], v[78:81], v[20:35]
	v_add_f32_e64 v70, v88, 0
	v_add_f32_e64 v71, v89, 0
	v_add_f32_e64 v70, v230, v70
	v_add_f32_e64 v71, v231, v71
	v_add_f32_e64 v70, v232, v70
	v_add_f32_e64 v71, v233, v71
	v_add_f32_e32 v70, v98, v70
	v_add_f32_e32 v71, v99, v71
	s_waitcnt lgkmcnt(0)
	v_mfma_f32_32x32x16_bf16 v[4:19], v[74:77], v[78:81], v[4:19]
	v_add_f32_e64 v70, v170, v70
	v_add_f32_e64 v71, v171, v71
	v_add_f32_e64 v70, v234, v70
	v_add_f32_e64 v71, v235, v71
	v_add_f32_e64 v70, v236, v70
	v_add_f32_e64 v71, v237, v71
	v_add_f32_e32 v70, v222, v70
	v_add_f32_e32 v71, v223, v71
	s_nop 0
	v_add_f32_e32 v70, v90, v70
	v_add_f32_e32 v71, v91, v71
	s_nop 0
	v_add_f32_e32 v70, v92, v70
	v_add_f32_e32 v71, v93, v71
	s_nop 0
	v_add_f32_e32 v70, v94, v70
	v_add_f32_e32 v71, v95, v71
	s_nop 0
	v_add_f32_e32 v70, v96, v70
	v_add_f32_e32 v71, v97, v71
	s_nop 0
	v_add_f32_e32 v70, v224, v70
	v_add_f32_e32 v71, v225, v71
	s_nop 0
	v_add_f32_e32 v70, v226, v70
	v_add_f32_e32 v71, v227, v71
	s_nop 0
	v_add_f32_e32 v70, v228, v70
	v_add_f32_e32 v71, v229, v71
	s_nop 0
	v_add_f32_e32 v70, v82, v70
	v_add_f32_e32 v71, v83, v71
	s_nop 0
	v_add_f32_e32 v3, v70, v71
	ds_bpermute_b32 v70, v179, v3
	s_waitcnt lgkmcnt(0)
	v_add_f32_e32 v3, v3, v70
	v_fmac_f32_e32 v3, v217, v68

.LBB0_1462:
	v_add_u32_e32 v3, v165, v196
	v_sub_f32_e32 v52, v52, v132
	v_sub_f32_e32 v53, v53, v132
	v_sub_f32_e32 v54, v54, v132
	v_sub_f32_e32 v55, v55, v132
	v_sub_f32_e32 v56, v56, v132
	v_sub_f32_e32 v57, v57, v132
	v_sub_f32_e32 v58, v58, v132
	v_sub_f32_e32 v59, v59, v132
	v_add_u32_e32 v69, v3, v190
	v_exp_f32_e32 v52, v52
	v_exp_f32_e32 v53, v53
	v_exp_f32_e32 v54, v54
	v_exp_f32_e32 v55, v55
	v_exp_f32_e32 v56, v56
	v_exp_f32_e32 v57, v57
	v_exp_f32_e32 v58, v58
	v_exp_f32_e32 v59, v59
	v_add_u32_e32 v69, 0x6800, v69
	ds_read2_b64 v[74:77], v69 offset0:64 offset1:66
	ds_read2_b64 v[78:81], v69 offset0:68 offset1:70
	v_add_u32_e32 v3, v3, v191
	v_cvt_pk_bf16_f32 v70, v52, v53
	v_cvt_pk_bf16_f32 v71, v54, v55
	v_cvt_pk_bf16_f32 v72, v56, v57
	v_cvt_pk_bf16_f32 v73, v58, v59
	v_add_u32_e32 v3, 0x6800, v3
	v_sub_f32_e32 v60, v60, v132
	v_sub_f32_e32 v61, v61, v132
	s_waitcnt lgkmcnt(1)
	v_mfma_f32_32x32x16_bf16 v[20:35], v[74:77], v[70:73], v[20:35]
	ds_read2_b64 v[74:77], v3 offset0:64 offset1:66
	ds_read2_b64 v[82:85], v3 offset0:68 offset1:70
	v_add_f32_e64 v62, v62, -v132
	v_add_f32_e64 v63, v63, -v132
	v_add_f32_e64 v64, v64, -v132
	v_add_f32_e64 v65, v65, -v132
	v_sub_f32_e32 v66, v66, v132
	v_sub_f32_e32 v67, v67, v132
	v_exp_f32_e32 v60, v60
	v_exp_f32_e32 v61, v61
	v_exp_f32_e32 v62, v62
	s_waitcnt lgkmcnt(1)
	v_mfma_f32_32x32x16_bf16 v[4:19], v[74:77], v[70:73], v[4:19]
	v_exp_f32_e32 v63, v63
	v_exp_f32_e32 v64, v64
	v_exp_f32_e32 v65, v65
	v_exp_f32_e32 v66, v66
	v_exp_f32_e32 v67, v67
	v_cvt_pk_bf16_f32 v70, v60, v61
	v_cvt_pk_bf16_f32 v71, v62, v63
	v_cvt_pk_bf16_f32 v72, v64, v65
	v_cvt_pk_bf16_f32 v73, v66, v67
	s_nop 1
	v_mfma_f32_32x32x16_bf16 v[20:35], v[78:81], v[70:73], v[20:35]
	s_waitcnt lgkmcnt(0)
	v_mfma_f32_32x32x16_bf16 v[4:19], v[82:85], v[70:73], v[4:19]
	v_add_f32_e64 v42, v42, -v132
	v_add_f32_e64 v43, v43, -v132
	v_add_f32_e64 v36, v36, -v132
	v_add_f32_e64 v37, v37, -v132
	v_add_f32_e64 v38, v38, -v132
	v_add_f32_e64 v39, v39, -v132
	v_sub_f32_e32 v40, v40, v132
	v_sub_f32_e32 v41, v41, v132
	v_exp_f32_e32 v78, v42
	v_exp_f32_e32 v79, v43
	v_sub_f32_e32 v42, v44, v132
	v_sub_f32_e32 v43, v45, v132
	v_exp_f32_e32 v36, v36
	v_exp_f32_e32 v37, v37
	v_exp_f32_e32 v38, v38
	v_exp_f32_e32 v39, v39
	v_exp_f32_e32 v40, v40
	v_exp_f32_e32 v41, v41
	v_exp_f32_e32 v80, v42
	v_exp_f32_e32 v81, v43
	v_sub_f32_e32 v42, v46, v132
	v_sub_f32_e32 v43, v47, v132
	v_cvt_pk_bf16_f32 v44, v40, v41
	v_exp_f32_e32 v82, v42
	v_exp_f32_e32 v83, v43
	v_sub_f32_e32 v42, v48, v132
	v_sub_f32_e32 v43, v49, v132
	ds_read2_b64 v[46:49], v69 offset0:72 offset1:74
	ds_read2_b64 v[70:73], v69 offset0:76 offset1:78
	v_exp_f32_e32 v84, v42
	v_exp_f32_e32 v85, v43
	v_sub_f32_e32 v42, v50, v132
	v_sub_f32_e32 v43, v51, v132
	v_cvt_pk_bf16_f32 v45, v78, v79
	v_exp_f32_e32 v50, v42
	v_exp_f32_e32 v51, v43
	v_cvt_pk_bf16_f32 v42, v36, v37
	v_cvt_pk_bf16_f32 v43, v38, v39
	s_waitcnt lgkmcnt(1)
	s_nop 0
	v_mfma_f32_32x32x16_bf16 v[20:35], v[46:49], v[42:45], v[20:35]
	ds_read2_b64 v[46:49], v3 offset0:72 offset1:74
	ds_read2_b64 v[74:77], v3 offset0:76 offset1:78
	s_waitcnt lgkmcnt(1)
	v_mfma_f32_32x32x16_bf16 v[4:19], v[46:49], v[42:45], v[4:19]
	v_cvt_pk_bf16_f32 v42, v80, v81
	v_cvt_pk_bf16_f32 v43, v82, v83
	v_cvt_pk_bf16_f32 v44, v84, v85
	v_cvt_pk_bf16_f32 v45, v50, v51
	s_nop 1
	v_mfma_f32_32x32x16_bf16 v[20:35], v[70:73], v[42:45], v[20:35]
	s_waitcnt lgkmcnt(0)
	v_mfma_f32_32x32x16_bf16 v[4:19], v[74:77], v[42:45], v[4:19]
	v_add_f32_e64 v42, v52, 0
	v_add_f32_e64 v43, v53, 0
	v_add_f32_e64 v42, v54, v42
	v_add_f32_e64 v43, v55, v43
	v_add_f32_e64 v42, v56, v42
	v_add_f32_e64 v43, v57, v43
	v_add_f32_e32 v42, v58, v42
	v_add_f32_e32 v43, v59, v43
	s_nop 0
	v_add_f32_e32 v42, v60, v42
	v_add_f32_e32 v43, v61, v43
	s_nop 0
	v_add_f32_e32 v42, v62, v42
	v_add_f32_e32 v43, v63, v43
	s_nop 0
	v_add_f32_e32 v42, v64, v42
	v_add_f32_e32 v43, v65, v43
	s_nop 0
	v_add_f32_e32 v42, v66, v42
	v_add_f32_e32 v43, v67, v43
	s_nop 0
	v_add_f32_e32 v36, v36, v42
	v_add_f32_e32 v37, v37, v43
	s_nop 0
	v_add_f32_e32 v36, v38, v36
	v_add_f32_e32 v37, v39, v37
	s_nop 0
	v_add_f32_e32 v36, v40, v36
	v_add_f32_e32 v37, v41, v37
	s_nop 0
	v_add_f32_e32 v36, v78, v36
	v_add_f32_e32 v37, v79, v37
	s_nop 0
	v_add_f32_e32 v36, v80, v36
	v_add_f32_e32 v37, v81, v37
	s_nop 0
	v_add_f32_e32 v36, v82, v36
	v_add_f32_e32 v37, v83, v37
	s_nop 0
	v_add_f32_e32 v36, v84, v36
	v_add_f32_e32 v37, v85, v37
	s_nop 0
	v_add_f32_e32 v36, v50, v36
	v_add_f32_e32 v37, v51, v37
	s_nop 0
	v_add_f32_e32 v3, v36, v37
	ds_bpermute_b32 v36, v179, v3
	s_waitcnt lgkmcnt(0)
	v_add_f32_e32 v3, v3, v36
	s_nop 0
	v_fmac_f32_e32 v3, v217, v68
	s_nop 6
	s_branch .LBB0_1464
